# attention K/V/rope-table staging: all global loads issued up front behind counted vmcnt waits instead of 19 serialized round trips per unit
# speedup vs baseline: 1.0052x; 1.0052x over previous
.LBB0_180:
	s_add_u32 s62, s60, 0xfffc0080
	s_addc_u32 s63, s61, -1
	s_add_i32 s86, 0, 0x10000
	s_cmp_eq_u32 s85, 12
	s_cselect_b32 vcc_hi, s47, s63
	s_cselect_b32 vcc_lo, s82, s62
	v_add_u32_e32 v142, s86, v145
	s_cselect_b32 s63, s21, s84
	s_cselect_b32 s62, s83, s89
	s_add_i32 s92, 0, 0x14000
	ds_read_b128 v[138:141], v142
	ds_read_b128 v[172:175], v142 offset:1024
	ds_read_b128 v[176:179], v142 offset:2048
	ds_read_b128 v[180:183], v142 offset:3072
	v_add_u32_e32 v142, s92, v145
	ds_read_b128 v[184:187], v142
	ds_read_b128 v[188:191], v142 offset:1024
	ds_read_b128 v[192:195], v142 offset:2048
	ds_read_b128 v[196:199], v142 offset:3072
	v_lshl_add_u64 v[142:143], s[60:61], 0, v[136:137]
	s_add_i32 m0, s68, 0xc000
	ds_read_b128 v[210:213], v148
	ds_read_b128 v[214:217], v148 offset:1024
	ds_read_b128 v[218:221], v148 offset:2048
	ds_read_b128 v[224:227], v148 offset:3072
	ds_read_b128 v[228:231], v148 offset:4096
	ds_read_b128 v[232:235], v148 offset:5120
	ds_read_b128 v[236:239], v148 offset:6144
	ds_read_b128 v[240:243], v148 offset:7168
	global_load_lds_dwordx4 v[142:143], off
	v_lshl_add_u64 v[142:143], s[60:61], 0, v[134:135]
	s_add_i32 m0, s68, 0xe000
	s_nop 0
	global_load_lds_dwordx4 v[142:143], off
	s_waitcnt vmcnt(8)
	s_waitcnt lgkmcnt(0)
	s_barrier
	s_setprio 1
	s_waitcnt lgkmcnt(0)
	v_mfma_f32_16x16x32_bf16 v[124:127], v[138:141], v[210:213], v[124:127]
	v_mfma_f32_16x16x32_bf16 v[116:119], v[176:179], v[210:213], v[116:119]
	v_mfma_f32_16x16x32_bf16 v[108:111], v[138:141], v[218:221], v[108:111]
	v_mfma_f32_16x16x32_bf16 v[100:103], v[176:179], v[218:221], v[100:103]
	v_mfma_f32_16x16x32_bf16 v[92:95], v[138:141], v[228:231], v[92:95]
	v_mfma_f32_16x16x32_bf16 v[84:87], v[176:179], v[228:231], v[84:87]
	v_mfma_f32_16x16x32_bf16 v[76:79], v[138:141], v[236:239], v[76:79]
	v_mfma_f32_16x16x32_bf16 v[68:71], v[176:179], v[236:239], v[68:71]
	v_mfma_f32_16x16x32_bf16 v[124:127], v[172:175], v[214:217], v[124:127]
	v_mfma_f32_16x16x32_bf16 v[116:119], v[180:183], v[214:217], v[116:119]
	v_mfma_f32_16x16x32_bf16 v[108:111], v[172:175], v[224:227], v[108:111]
	v_mfma_f32_16x16x32_bf16 v[100:103], v[180:183], v[224:227], v[100:103]
	v_mfma_f32_16x16x32_bf16 v[92:95], v[172:175], v[232:235], v[92:95]
	v_mfma_f32_16x16x32_bf16 v[84:87], v[180:183], v[232:235], v[84:87]
	v_mfma_f32_16x16x32_bf16 v[76:79], v[172:175], v[240:243], v[76:79]
	v_mfma_f32_16x16x32_bf16 v[68:71], v[180:183], v[240:243], v[68:71]
	s_setprio 0
	s_setprio 1
	v_mfma_f32_16x16x32_bf16 v[120:123], v[184:187], v[210:213], v[120:123]
	v_mfma_f32_16x16x32_bf16 v[112:115], v[192:195], v[210:213], v[112:115]
	v_mfma_f32_16x16x32_bf16 v[104:107], v[184:187], v[218:221], v[104:107]
	v_mfma_f32_16x16x32_bf16 v[96:99], v[192:195], v[218:221], v[96:99]
	v_mfma_f32_16x16x32_bf16 v[88:91], v[184:187], v[228:231], v[88:91]
	v_mfma_f32_16x16x32_bf16 v[80:83], v[192:195], v[228:231], v[80:83]
	v_mfma_f32_16x16x32_bf16 v[72:75], v[184:187], v[236:239], v[72:75]
	v_mfma_f32_16x16x32_bf16 v[64:67], v[192:195], v[236:239], v[64:67]
	v_mfma_f32_16x16x32_bf16 v[120:123], v[188:191], v[214:217], v[120:123]
	v_mfma_f32_16x16x32_bf16 v[112:115], v[196:199], v[214:217], v[112:115]
	v_mfma_f32_16x16x32_bf16 v[104:107], v[188:191], v[224:227], v[104:107]
	v_mfma_f32_16x16x32_bf16 v[96:99], v[196:199], v[224:227], v[96:99]
	v_mfma_f32_16x16x32_bf16 v[88:91], v[188:191], v[232:235], v[88:91]
	v_mfma_f32_16x16x32_bf16 v[80:83], v[196:199], v[232:235], v[80:83]
	v_mfma_f32_16x16x32_bf16 v[72:75], v[188:191], v[240:243], v[72:75]
	v_mfma_f32_16x16x32_bf16 v[64:67], v[196:199], v[240:243], v[64:67]
	s_setprio 0
	s_barrier
	s_add_i32 s86, s86, s67
	v_lshl_add_u64 v[142:143], s[62:63], 0, v[152:153]
	s_mov_b32 m0, s86
	ds_read_b128 v[210:213], v148 offset:16384
	ds_read_b128 v[214:217], v148 offset:17408
	ds_read_b128 v[218:221], v148 offset:18432
	ds_read_b128 v[224:227], v148 offset:19456
	ds_read_b128 v[228:231], v148 offset:20480
	ds_read_b128 v[232:235], v148 offset:21504
	ds_read_b128 v[236:239], v148 offset:22528
	ds_read_b128 v[240:243], v148 offset:23552
	global_load_lds_dwordx4 v[142:143], off
	s_add_i32 m0, s86, 0x2000
	s_add_u32 s86, s62, 0x40000
	v_lshl_add_u64 v[150:151], s[62:63], 0, v[128:129]
	s_addc_u32 s87, s63, 0
	s_add_i32 s92, s92, s67
	global_load_lds_dwordx4 v[150:151], off
	v_lshl_add_u64 v[244:245], s[86:87], 0, v[152:153]
	s_mov_b32 m0, s92
	v_lshl_add_u64 v[246:247], vcc, 0, v[130:131]
	global_load_lds_dwordx4 v[244:245], off
	v_lshl_add_u64 v[244:245], s[86:87], 0, v[128:129]
	s_add_i32 m0, s92, 0x2000
	s_nop 0
	global_load_lds_dwordx4 v[244:245], off
	v_lshl_add_u64 v[244:245], vcc, 0, v[132:133]
	s_mov_b32 m0, s68
	s_nop 0
	global_load_lds_dwordx4 v[244:245], off
	s_mov_b32 m0, s69
	s_nop 0
	global_load_lds_dwordx4 v[246:247], off
	s_waitcnt vmcnt(8)
	s_waitcnt lgkmcnt(0)
	s_barrier
	s_setprio 1
	s_waitcnt lgkmcnt(0)
	v_mfma_f32_16x16x32_bf16 v[60:63], v[138:141], v[210:213], v[60:63]
	v_mfma_f32_16x16x32_bf16 v[52:55], v[176:179], v[210:213], v[52:55]
	v_mfma_f32_16x16x32_bf16 v[44:47], v[138:141], v[218:221], v[44:47]
	v_mfma_f32_16x16x32_bf16 v[36:39], v[176:179], v[218:221], v[36:39]
	v_mfma_f32_16x16x32_bf16 v[28:31], v[138:141], v[228:231], v[28:31]
	v_mfma_f32_16x16x32_bf16 v[20:23], v[176:179], v[228:231], v[20:23]
	v_mfma_f32_16x16x32_bf16 v[12:15], v[138:141], v[236:239], v[12:15]
	v_mfma_f32_16x16x32_bf16 v[4:7], v[176:179], v[236:239], v[4:7]
	v_mfma_f32_16x16x32_bf16 v[60:63], v[172:175], v[214:217], v[60:63]
	v_mfma_f32_16x16x32_bf16 v[52:55], v[180:183], v[214:217], v[52:55]
	v_mfma_f32_16x16x32_bf16 v[44:47], v[172:175], v[224:227], v[44:47]
	v_mfma_f32_16x16x32_bf16 v[36:39], v[180:183], v[224:227], v[36:39]
	v_mfma_f32_16x16x32_bf16 v[28:31], v[172:175], v[232:235], v[28:31]
	v_mfma_f32_16x16x32_bf16 v[20:23], v[180:183], v[232:235], v[20:23]
	v_mfma_f32_16x16x32_bf16 v[12:15], v[172:175], v[240:243], v[12:15]
	v_mfma_f32_16x16x32_bf16 v[4:7], v[180:183], v[240:243], v[4:7]
	s_setprio 0
	s_setprio 1
	v_mfma_f32_16x16x32_bf16 v[56:59], v[184:187], v[210:213], v[56:59]
	v_mfma_f32_16x16x32_bf16 v[48:51], v[192:195], v[210:213], v[48:51]
	v_mfma_f32_16x16x32_bf16 v[40:43], v[184:187], v[218:221], v[40:43]
	v_mfma_f32_16x16x32_bf16 v[32:35], v[192:195], v[218:221], v[32:35]
	v_mfma_f32_16x16x32_bf16 v[24:27], v[184:187], v[228:231], v[24:27]
	v_mfma_f32_16x16x32_bf16 v[16:19], v[192:195], v[228:231], v[16:19]
	v_mfma_f32_16x16x32_bf16 v[8:11], v[184:187], v[236:239], v[8:11]
	v_mfma_f32_16x16x32_bf16 v[0:3], v[192:195], v[236:239], v[0:3]
	v_mfma_f32_16x16x32_bf16 v[56:59], v[188:191], v[214:217], v[56:59]
	v_mfma_f32_16x16x32_bf16 v[48:51], v[196:199], v[214:217], v[48:51]
	v_mfma_f32_16x16x32_bf16 v[40:43], v[188:191], v[224:227], v[40:43]
	v_mfma_f32_16x16x32_bf16 v[32:35], v[196:199], v[224:227], v[32:35]
	v_mfma_f32_16x16x32_bf16 v[24:27], v[188:191], v[232:235], v[24:27]
	v_mfma_f32_16x16x32_bf16 v[16:19], v[196:199], v[232:235], v[16:19]
	v_mfma_f32_16x16x32_bf16 v[8:11], v[188:191], v[240:243], v[8:11]
	v_mfma_f32_16x16x32_bf16 v[0:3], v[196:199], v[240:243], v[0:3]
	s_setprio 0
	s_barrier
	s_add_i32 s92, 0, 0x18000
	v_add_u32_e32 v149, s92, v145
	s_add_i32 s93, 0, 0x1c000
	ds_read_b128 v[138:141], v149
	ds_read_b128 v[172:175], v149 offset:1024
	ds_read_b128 v[176:179], v149 offset:2048
	ds_read_b128 v[180:183], v149 offset:3072
	v_add_u32_e32 v149, s93, v145
	ds_read_b128 v[184:187], v149
	ds_read_b128 v[188:191], v149 offset:1024
	ds_read_b128 v[192:195], v149 offset:2048
	ds_read_b128 v[196:199], v149 offset:3072
	s_add_u32 s86, vcc_lo, 0x40000
	s_addc_u32 s87, vcc_hi, 0
	s_mov_b32 m0, s74
	v_lshl_add_u64 v[248:249], s[86:87], 0, v[132:133]
	ds_read_b128 v[210:213], v148 offset:32768
	ds_read_b128 v[214:217], v148 offset:33792
	ds_read_b128 v[218:221], v148 offset:34816
	ds_read_b128 v[224:227], v148 offset:35840
	ds_read_b128 v[228:231], v148 offset:36864
	ds_read_b128 v[232:235], v148 offset:37888
	ds_read_b128 v[236:239], v148 offset:38912
	ds_read_b128 v[240:243], v148 offset:39936
	global_load_lds_dwordx4 v[248:249], off
	v_lshl_add_u64 v[248:249], s[86:87], 0, v[130:131]
	s_mov_b32 m0, s75
	s_nop 0
	global_load_lds_dwordx4 v[248:249], off
	s_waitcnt vmcnt(8)
	s_waitcnt lgkmcnt(0)
	s_barrier
	s_setprio 1
	s_waitcnt lgkmcnt(0)
	v_mfma_f32_16x16x32_bf16 v[124:127], v[138:141], v[210:213], v[124:127]
	v_mfma_f32_16x16x32_bf16 v[116:119], v[176:179], v[210:213], v[116:119]
	v_mfma_f32_16x16x32_bf16 v[108:111], v[138:141], v[218:221], v[108:111]
	v_mfma_f32_16x16x32_bf16 v[100:103], v[176:179], v[218:221], v[100:103]
	v_mfma_f32_16x16x32_bf16 v[92:95], v[138:141], v[228:231], v[92:95]
	v_mfma_f32_16x16x32_bf16 v[84:87], v[176:179], v[228:231], v[84:87]
	v_mfma_f32_16x16x32_bf16 v[76:79], v[138:141], v[236:239], v[76:79]
	v_mfma_f32_16x16x32_bf16 v[68:71], v[176:179], v[236:239], v[68:71]
	v_mfma_f32_16x16x32_bf16 v[124:127], v[172:175], v[214:217], v[124:127]
	v_mfma_f32_16x16x32_bf16 v[116:119], v[180:183], v[214:217], v[116:119]
	v_mfma_f32_16x16x32_bf16 v[108:111], v[172:175], v[224:227], v[108:111]
	v_mfma_f32_16x16x32_bf16 v[100:103], v[180:183], v[224:227], v[100:103]
	v_mfma_f32_16x16x32_bf16 v[92:95], v[172:175], v[232:235], v[92:95]
	v_mfma_f32_16x16x32_bf16 v[84:87], v[180:183], v[232:235], v[84:87]
	v_mfma_f32_16x16x32_bf16 v[76:79], v[172:175], v[240:243], v[76:79]
	v_mfma_f32_16x16x32_bf16 v[68:71], v[180:183], v[240:243], v[68:71]
	s_setprio 0
	s_setprio 1
	v_mfma_f32_16x16x32_bf16 v[120:123], v[184:187], v[210:213], v[120:123]
	v_mfma_f32_16x16x32_bf16 v[112:115], v[192:195], v[210:213], v[112:115]
	v_mfma_f32_16x16x32_bf16 v[104:107], v[184:187], v[218:221], v[104:107]
	v_mfma_f32_16x16x32_bf16 v[96:99], v[192:195], v[218:221], v[96:99]
	v_mfma_f32_16x16x32_bf16 v[88:91], v[184:187], v[228:231], v[88:91]
	v_mfma_f32_16x16x32_bf16 v[80:83], v[192:195], v[228:231], v[80:83]
	v_mfma_f32_16x16x32_bf16 v[72:75], v[184:187], v[236:239], v[72:75]
	v_mfma_f32_16x16x32_bf16 v[64:67], v[192:195], v[236:239], v[64:67]
	v_mfma_f32_16x16x32_bf16 v[120:123], v[188:191], v[214:217], v[120:123]
	v_mfma_f32_16x16x32_bf16 v[112:115], v[196:199], v[214:217], v[112:115]
	v_mfma_f32_16x16x32_bf16 v[104:107], v[188:191], v[224:227], v[104:107]
	v_mfma_f32_16x16x32_bf16 v[96:99], v[196:199], v[224:227], v[96:99]
	v_mfma_f32_16x16x32_bf16 v[88:91], v[188:191], v[232:235], v[88:91]
	v_mfma_f32_16x16x32_bf16 v[80:83], v[196:199], v[232:235], v[80:83]
	v_mfma_f32_16x16x32_bf16 v[72:75], v[188:191], v[240:243], v[72:75]
	v_mfma_f32_16x16x32_bf16 v[64:67], v[196:199], v[240:243], v[64:67]
	s_setprio 0
	s_barrier
	s_add_i32 s86, s92, s67
	v_lshl_add_u64 v[142:143], v[142:143], 0, s[22:23]
	s_mov_b32 m0, s86
	ds_read_b128 v[210:213], v148 offset:49152
	ds_read_b128 v[214:217], v148 offset:50176
	ds_read_b128 v[218:221], v148 offset:51200
	ds_read_b128 v[224:227], v148 offset:52224
	ds_read_b128 v[228:231], v148 offset:53248
	ds_read_b128 v[232:235], v148 offset:54272
	ds_read_b128 v[236:239], v148 offset:55296
	ds_read_b128 v[240:243], v148 offset:56320
	global_load_lds_dwordx4 v[142:143], off
	s_add_i32 m0, s86, 0x2000
	s_add_u32 s62, s62, 0x40080
	v_lshl_add_u64 v[142:143], v[150:151], 0, s[22:23]
	s_addc_u32 s63, s63, 0
	s_add_i32 s86, s93, s67
	global_load_lds_dwordx4 v[142:143], off
	v_lshl_add_u64 v[142:143], s[62:63], 0, v[152:153]
	s_mov_b32 m0, s86
	s_nop 0
	global_load_lds_dwordx4 v[142:143], off
	v_lshl_add_u64 v[142:143], s[62:63], 0, v[128:129]
	s_add_i32 m0, s86, 0x2000
	s_nop 0
	global_load_lds_dwordx4 v[142:143], off
	v_lshl_add_u64 v[142:143], v[244:245], 0, s[22:23]
	s_mov_b32 m0, s77
	s_nop 0
	global_load_lds_dwordx4 v[142:143], off
	v_lshl_add_u64 v[142:143], v[246:247], 0, s[22:23]
	s_mov_b32 m0, s78
	s_nop 0
	global_load_lds_dwordx4 v[142:143], off
	s_waitcnt vmcnt(8)
	s_waitcnt lgkmcnt(0)
	s_barrier
	s_setprio 1
	s_waitcnt lgkmcnt(0)
	v_mfma_f32_16x16x32_bf16 v[60:63], v[138:141], v[210:213], v[60:63]
	v_mfma_f32_16x16x32_bf16 v[52:55], v[176:179], v[210:213], v[52:55]
	v_mfma_f32_16x16x32_bf16 v[44:47], v[138:141], v[218:221], v[44:47]
	v_mfma_f32_16x16x32_bf16 v[36:39], v[176:179], v[218:221], v[36:39]
	v_mfma_f32_16x16x32_bf16 v[28:31], v[138:141], v[228:231], v[28:31]
	v_mfma_f32_16x16x32_bf16 v[20:23], v[176:179], v[228:231], v[20:23]
	v_mfma_f32_16x16x32_bf16 v[12:15], v[138:141], v[236:239], v[12:15]
	v_mfma_f32_16x16x32_bf16 v[4:7], v[176:179], v[236:239], v[4:7]
	v_mfma_f32_16x16x32_bf16 v[60:63], v[172:175], v[214:217], v[60:63]
	v_mfma_f32_16x16x32_bf16 v[52:55], v[180:183], v[214:217], v[52:55]
	v_mfma_f32_16x16x32_bf16 v[44:47], v[172:175], v[224:227], v[44:47]
	v_mfma_f32_16x16x32_bf16 v[36:39], v[180:183], v[224:227], v[36:39]
	v_mfma_f32_16x16x32_bf16 v[28:31], v[172:175], v[232:235], v[28:31]
	v_mfma_f32_16x16x32_bf16 v[20:23], v[180:183], v[232:235], v[20:23]
	v_mfma_f32_16x16x32_bf16 v[12:15], v[172:175], v[240:243], v[12:15]
	v_mfma_f32_16x16x32_bf16 v[4:7], v[180:183], v[240:243], v[4:7]
	s_setprio 0
	s_setprio 1
	v_mfma_f32_16x16x32_bf16 v[56:59], v[184:187], v[210:213], v[56:59]
	v_mfma_f32_16x16x32_bf16 v[48:51], v[192:195], v[210:213], v[48:51]
	v_mfma_f32_16x16x32_bf16 v[40:43], v[184:187], v[218:221], v[40:43]
	v_mfma_f32_16x16x32_bf16 v[32:35], v[192:195], v[218:221], v[32:35]
	v_mfma_f32_16x16x32_bf16 v[24:27], v[184:187], v[228:231], v[24:27]
	v_mfma_f32_16x16x32_bf16 v[16:19], v[192:195], v[228:231], v[16:19]
	v_mfma_f32_16x16x32_bf16 v[8:11], v[184:187], v[236:239], v[8:11]
	v_mfma_f32_16x16x32_bf16 v[0:3], v[192:195], v[236:239], v[0:3]
	v_mfma_f32_16x16x32_bf16 v[56:59], v[188:191], v[214:217], v[56:59]
	v_mfma_f32_16x16x32_bf16 v[48:51], v[196:199], v[214:217], v[48:51]
	v_mfma_f32_16x16x32_bf16 v[40:43], v[188:191], v[224:227], v[40:43]
	v_mfma_f32_16x16x32_bf16 v[32:35], v[196:199], v[224:227], v[32:35]
	v_mfma_f32_16x16x32_bf16 v[24:27], v[188:191], v[232:235], v[24:27]
	v_mfma_f32_16x16x32_bf16 v[16:19], v[196:199], v[232:235], v[16:19]
	v_mfma_f32_16x16x32_bf16 v[8:11], v[188:191], v[240:243], v[8:11]
	v_mfma_f32_16x16x32_bf16 v[0:3], v[196:199], v[240:243], v[0:3]
	s_setprio 0
	s_barrier
	s_add_i32 s85, s85, 2
	s_add_u32 s89, s89, 0x100
	s_addc_u32 s84, s84, 0
	s_add_u32 s60, s60, 0x100
	s_addc_u32 s61, s61, 0
	s_cmp_gt_u32 s85, 13
	s_cbranch_scc0 .LBB0_180
	s_and_b64 vcc, exec, s[18:19]
	s_cbranch_vccz .LBB0_183
	s_barrier

.LBB0_281:
	s_add_u32 vcc_lo, s60, 0x100
	s_addc_u32 vcc_hi, s61, 0
	s_add_i32 s87, 0, 0x10000
	s_cmp_eq_u32 s86, 40
	s_cselect_b32 s67, s51, vcc_hi
	s_cselect_b32 s66, s50, vcc_lo
	s_cselect_b32 s19, s45, s85
	s_cselect_b32 s18, s44, s84
	s_add_i32 s92, 0, 0x14000
	v_add_u32_e32 v140, s87, v210
	v_add_u32_e32 v186, s92, v210
	ds_read_b128 v[128:131], v140
	ds_read_b128 v[132:135], v140 offset:1024
	ds_read_b128 v[136:139], v140 offset:2048
	ds_read_b128 v[140:143], v140 offset:3072
	ds_read_b128 v[144:147], v186
	ds_read_b128 v[148:151], v186 offset:1024
	ds_read_b128 v[182:185], v186 offset:2048
	ds_read_b128 v[186:189], v186 offset:3072
	v_lshl_add_u64 v[198:199], s[60:61], 0, v[180:181]
	s_add_i32 m0, s69, 0xc000
	ds_read_b128 v[190:193], v212
	ds_read_b128 v[194:197], v212 offset:1024
	ds_read_b128 v[214:217], v212 offset:2048
	ds_read_b128 v[218:221], v212 offset:3072
	ds_read_b128 v[224:227], v212 offset:4096
	ds_read_b128 v[228:231], v212 offset:5120
	ds_read_b128 v[232:235], v212 offset:6144
	ds_read_b128 v[236:239], v212 offset:7168
	global_load_lds_dwordx4 v[198:199], off
	v_lshl_add_u64 v[198:199], s[60:61], 0, v[178:179]
	s_add_i32 m0, s69, 0xe000
	s_nop 0
	global_load_lds_dwordx4 v[198:199], off
	s_waitcnt vmcnt(8)
	s_waitcnt lgkmcnt(0)
	s_barrier
	s_setprio 1
	s_waitcnt lgkmcnt(0)
	v_mfma_f32_16x16x32_bf16 v[124:127], v[128:131], v[190:193], v[124:127]
	v_mfma_f32_16x16x32_bf16 v[120:123], v[136:139], v[190:193], v[120:123]
	v_mfma_f32_16x16x32_bf16 v[108:111], v[128:131], v[214:217], v[108:111]
	v_mfma_f32_16x16x32_bf16 v[104:107], v[136:139], v[214:217], v[104:107]
	v_mfma_f32_16x16x32_bf16 v[92:95], v[128:131], v[224:227], v[92:95]
	v_mfma_f32_16x16x32_bf16 v[88:91], v[136:139], v[224:227], v[88:91]
	v_mfma_f32_16x16x32_bf16 v[76:79], v[128:131], v[232:235], v[76:79]
	v_mfma_f32_16x16x32_bf16 v[72:75], v[136:139], v[232:235], v[72:75]
	v_mfma_f32_16x16x32_bf16 v[124:127], v[132:135], v[194:197], v[124:127]
	v_mfma_f32_16x16x32_bf16 v[120:123], v[140:143], v[194:197], v[120:123]
	v_mfma_f32_16x16x32_bf16 v[108:111], v[132:135], v[218:221], v[108:111]
	v_mfma_f32_16x16x32_bf16 v[104:107], v[140:143], v[218:221], v[104:107]
	v_mfma_f32_16x16x32_bf16 v[92:95], v[132:135], v[228:231], v[92:95]
	v_mfma_f32_16x16x32_bf16 v[88:91], v[140:143], v[228:231], v[88:91]
	v_mfma_f32_16x16x32_bf16 v[76:79], v[132:135], v[236:239], v[76:79]
	v_mfma_f32_16x16x32_bf16 v[72:75], v[140:143], v[236:239], v[72:75]
	s_setprio 0
	s_setprio 1
	v_mfma_f32_16x16x32_bf16 v[116:119], v[144:147], v[190:193], v[116:119]
	v_mfma_f32_16x16x32_bf16 v[112:115], v[182:185], v[190:193], v[112:115]
	v_mfma_f32_16x16x32_bf16 v[100:103], v[144:147], v[214:217], v[100:103]
	v_mfma_f32_16x16x32_bf16 v[96:99], v[182:185], v[214:217], v[96:99]
	v_mfma_f32_16x16x32_bf16 v[84:87], v[144:147], v[224:227], v[84:87]
	v_mfma_f32_16x16x32_bf16 v[80:83], v[182:185], v[224:227], v[80:83]
	v_mfma_f32_16x16x32_bf16 v[68:71], v[144:147], v[232:235], v[68:71]
	v_mfma_f32_16x16x32_bf16 v[64:67], v[182:185], v[232:235], v[64:67]
	v_mfma_f32_16x16x32_bf16 v[116:119], v[148:151], v[194:197], v[116:119]
	v_mfma_f32_16x16x32_bf16 v[112:115], v[186:189], v[194:197], v[112:115]
	v_mfma_f32_16x16x32_bf16 v[100:103], v[148:151], v[218:221], v[100:103]
	v_mfma_f32_16x16x32_bf16 v[96:99], v[186:189], v[218:221], v[96:99]
	v_mfma_f32_16x16x32_bf16 v[84:87], v[148:151], v[228:231], v[84:87]
	v_mfma_f32_16x16x32_bf16 v[80:83], v[186:189], v[228:231], v[80:83]
	v_mfma_f32_16x16x32_bf16 v[68:71], v[148:151], v[236:239], v[68:71]
	v_mfma_f32_16x16x32_bf16 v[64:67], v[186:189], v[236:239], v[64:67]
	s_setprio 0
	s_barrier
	s_add_i32 s60, s87, s68
	v_lshl_add_u64 v[198:199], s[18:19], 0, v[152:153]
	s_mov_b32 m0, s60
	ds_read_b128 v[190:193], v212 offset:16384
	ds_read_b128 v[194:197], v212 offset:17408
	ds_read_b128 v[214:217], v212 offset:18432
	ds_read_b128 v[218:221], v212 offset:19456
	ds_read_b128 v[224:227], v212 offset:20480
	ds_read_b128 v[228:231], v212 offset:21504
	ds_read_b128 v[232:235], v212 offset:22528
	ds_read_b128 v[236:239], v212 offset:23552
	global_load_lds_dwordx4 v[198:199], off
	s_add_i32 m0, s60, 0x2000
	s_add_u32 s60, s18, 0xb0000
	v_lshl_add_u64 v[240:241], s[18:19], 0, v[172:173]
	s_addc_u32 s61, s19, 0
	s_add_i32 s87, s92, s68
	global_load_lds_dwordx4 v[240:241], off
	v_lshl_add_u64 v[242:243], s[60:61], 0, v[152:153]
	s_mov_b32 m0, s87
	v_lshl_add_u64 v[244:245], s[66:67], 0, v[174:175]
	global_load_lds_dwordx4 v[242:243], off
	v_lshl_add_u64 v[242:243], s[60:61], 0, v[172:173]
	s_add_i32 m0, s87, 0x2000
	s_nop 0
	global_load_lds_dwordx4 v[242:243], off
	v_lshl_add_u64 v[242:243], s[66:67], 0, v[176:177]
	s_mov_b32 m0, s69
	s_nop 0
	global_load_lds_dwordx4 v[242:243], off
	s_mov_b32 m0, s74
	s_nop 0
	global_load_lds_dwordx4 v[244:245], off
	s_waitcnt vmcnt(8)
	s_waitcnt lgkmcnt(0)
	s_barrier
	s_setprio 1
	s_waitcnt lgkmcnt(0)
	v_mfma_f32_16x16x32_bf16 v[60:63], v[128:131], v[190:193], v[60:63]
	v_mfma_f32_16x16x32_bf16 v[56:59], v[136:139], v[190:193], v[56:59]
	v_mfma_f32_16x16x32_bf16 v[44:47], v[128:131], v[214:217], v[44:47]
	v_mfma_f32_16x16x32_bf16 v[40:43], v[136:139], v[214:217], v[40:43]
	v_mfma_f32_16x16x32_bf16 v[28:31], v[128:131], v[224:227], v[28:31]
	v_mfma_f32_16x16x32_bf16 v[24:27], v[136:139], v[224:227], v[24:27]
	v_mfma_f32_16x16x32_bf16 v[12:15], v[128:131], v[232:235], v[12:15]
	v_mfma_f32_16x16x32_bf16 v[8:11], v[136:139], v[232:235], v[8:11]
	v_mfma_f32_16x16x32_bf16 v[60:63], v[132:135], v[194:197], v[60:63]
	v_mfma_f32_16x16x32_bf16 v[56:59], v[140:143], v[194:197], v[56:59]
	v_mfma_f32_16x16x32_bf16 v[44:47], v[132:135], v[218:221], v[44:47]
	v_mfma_f32_16x16x32_bf16 v[40:43], v[140:143], v[218:221], v[40:43]
	v_mfma_f32_16x16x32_bf16 v[28:31], v[132:135], v[228:231], v[28:31]
	v_mfma_f32_16x16x32_bf16 v[24:27], v[140:143], v[228:231], v[24:27]
	v_mfma_f32_16x16x32_bf16 v[12:15], v[132:135], v[236:239], v[12:15]
	v_mfma_f32_16x16x32_bf16 v[8:11], v[140:143], v[236:239], v[8:11]
	s_setprio 0
	s_setprio 1
	v_mfma_f32_16x16x32_bf16 v[52:55], v[144:147], v[190:193], v[52:55]
	v_mfma_f32_16x16x32_bf16 v[48:51], v[182:185], v[190:193], v[48:51]
	v_mfma_f32_16x16x32_bf16 v[36:39], v[144:147], v[214:217], v[36:39]
	v_mfma_f32_16x16x32_bf16 v[32:35], v[182:185], v[214:217], v[32:35]
	v_mfma_f32_16x16x32_bf16 v[20:23], v[144:147], v[224:227], v[20:23]
	v_mfma_f32_16x16x32_bf16 v[16:19], v[182:185], v[224:227], v[16:19]
	v_mfma_f32_16x16x32_bf16 v[4:7], v[144:147], v[232:235], v[4:7]
	v_mfma_f32_16x16x32_bf16 v[0:3], v[182:185], v[232:235], v[0:3]
	v_mfma_f32_16x16x32_bf16 v[52:55], v[148:151], v[194:197], v[52:55]
	v_mfma_f32_16x16x32_bf16 v[48:51], v[186:189], v[194:197], v[48:51]
	v_mfma_f32_16x16x32_bf16 v[36:39], v[148:151], v[218:221], v[36:39]
	v_mfma_f32_16x16x32_bf16 v[32:35], v[186:189], v[218:221], v[32:35]
	v_mfma_f32_16x16x32_bf16 v[20:23], v[148:151], v[228:231], v[20:23]
	v_mfma_f32_16x16x32_bf16 v[16:19], v[186:189], v[228:231], v[16:19]
	v_mfma_f32_16x16x32_bf16 v[4:7], v[148:151], v[236:239], v[4:7]
	v_mfma_f32_16x16x32_bf16 v[0:3], v[186:189], v[236:239], v[0:3]
	s_setprio 0
	s_barrier
	s_add_i32 s87, 0, 0x18000
	s_add_i32 s92, 0, 0x1c000
	v_add_u32_e32 v140, s87, v210
	v_add_u32_e32 v186, s92, v210
	ds_read_b128 v[128:131], v140
	ds_read_b128 v[132:135], v140 offset:1024
	ds_read_b128 v[136:139], v140 offset:2048
	ds_read_b128 v[140:143], v140 offset:3072
	ds_read_b128 v[144:147], v186
	ds_read_b128 v[148:151], v186 offset:1024
	ds_read_b128 v[182:185], v186 offset:2048
	ds_read_b128 v[186:189], v186 offset:3072
	s_add_u32 s60, s66, 0xb0000
	s_addc_u32 s61, s67, 0
	s_mov_b32 m0, s75
	v_lshl_add_u64 v[246:247], s[60:61], 0, v[176:177]
	ds_read_b128 v[190:193], v212 offset:32768
	ds_read_b128 v[194:197], v212 offset:33792
	ds_read_b128 v[214:217], v212 offset:34816
	ds_read_b128 v[218:221], v212 offset:35840
	ds_read_b128 v[224:227], v212 offset:36864
	ds_read_b128 v[228:231], v212 offset:37888
	ds_read_b128 v[232:235], v212 offset:38912
	ds_read_b128 v[236:239], v212 offset:39936
	global_load_lds_dwordx4 v[246:247], off
	v_lshl_add_u64 v[246:247], s[60:61], 0, v[174:175]
	s_mov_b32 m0, s76
	s_nop 0
	global_load_lds_dwordx4 v[246:247], off
	s_waitcnt vmcnt(8)
	s_waitcnt lgkmcnt(0)
	s_barrier
	s_setprio 1
	s_waitcnt lgkmcnt(0)
	v_mfma_f32_16x16x32_bf16 v[124:127], v[128:131], v[190:193], v[124:127]
	v_mfma_f32_16x16x32_bf16 v[120:123], v[136:139], v[190:193], v[120:123]
	v_mfma_f32_16x16x32_bf16 v[108:111], v[128:131], v[214:217], v[108:111]
	v_mfma_f32_16x16x32_bf16 v[104:107], v[136:139], v[214:217], v[104:107]
	v_mfma_f32_16x16x32_bf16 v[92:95], v[128:131], v[224:227], v[92:95]
	v_mfma_f32_16x16x32_bf16 v[88:91], v[136:139], v[224:227], v[88:91]
	v_mfma_f32_16x16x32_bf16 v[76:79], v[128:131], v[232:235], v[76:79]
	v_mfma_f32_16x16x32_bf16 v[72:75], v[136:139], v[232:235], v[72:75]
	v_mfma_f32_16x16x32_bf16 v[124:127], v[132:135], v[194:197], v[124:127]
	v_mfma_f32_16x16x32_bf16 v[120:123], v[140:143], v[194:197], v[120:123]
	v_mfma_f32_16x16x32_bf16 v[108:111], v[132:135], v[218:221], v[108:111]
	v_mfma_f32_16x16x32_bf16 v[104:107], v[140:143], v[218:221], v[104:107]
	v_mfma_f32_16x16x32_bf16 v[92:95], v[132:135], v[228:231], v[92:95]
	v_mfma_f32_16x16x32_bf16 v[88:91], v[140:143], v[228:231], v[88:91]
	v_mfma_f32_16x16x32_bf16 v[76:79], v[132:135], v[236:239], v[76:79]
	v_mfma_f32_16x16x32_bf16 v[72:75], v[140:143], v[236:239], v[72:75]
	s_setprio 0
	s_setprio 1
	v_mfma_f32_16x16x32_bf16 v[116:119], v[144:147], v[190:193], v[116:119]
	v_mfma_f32_16x16x32_bf16 v[112:115], v[182:185], v[190:193], v[112:115]
	v_mfma_f32_16x16x32_bf16 v[100:103], v[144:147], v[214:217], v[100:103]
	v_mfma_f32_16x16x32_bf16 v[96:99], v[182:185], v[214:217], v[96:99]
	v_mfma_f32_16x16x32_bf16 v[84:87], v[144:147], v[224:227], v[84:87]
	v_mfma_f32_16x16x32_bf16 v[80:83], v[182:185], v[224:227], v[80:83]
	v_mfma_f32_16x16x32_bf16 v[68:71], v[144:147], v[232:235], v[68:71]
	v_mfma_f32_16x16x32_bf16 v[64:67], v[182:185], v[232:235], v[64:67]
	v_mfma_f32_16x16x32_bf16 v[116:119], v[148:151], v[194:197], v[116:119]
	v_mfma_f32_16x16x32_bf16 v[112:115], v[186:189], v[194:197], v[112:115]
	v_mfma_f32_16x16x32_bf16 v[100:103], v[148:151], v[218:221], v[100:103]
	v_mfma_f32_16x16x32_bf16 v[96:99], v[186:189], v[218:221], v[96:99]
	v_mfma_f32_16x16x32_bf16 v[84:87], v[148:151], v[228:231], v[84:87]
	v_mfma_f32_16x16x32_bf16 v[80:83], v[186:189], v[228:231], v[80:83]
	v_mfma_f32_16x16x32_bf16 v[68:71], v[148:151], v[236:239], v[68:71]
	v_mfma_f32_16x16x32_bf16 v[64:67], v[186:189], v[236:239], v[64:67]
	s_setprio 0
	s_barrier
	s_add_i32 s60, s87, s68
	v_lshl_add_u64 v[198:199], v[198:199], 0, s[22:23]
	s_mov_b32 m0, s60
	ds_read_b128 v[190:193], v212 offset:49152
	ds_read_b128 v[194:197], v212 offset:50176
	ds_read_b128 v[214:217], v212 offset:51200
	ds_read_b128 v[218:221], v212 offset:52224
	ds_read_b128 v[224:227], v212 offset:53248
	ds_read_b128 v[228:231], v212 offset:54272
	ds_read_b128 v[232:235], v212 offset:55296
	ds_read_b128 v[236:239], v212 offset:56320
	global_load_lds_dwordx4 v[198:199], off
	s_add_i32 m0, s60, 0x2000
	s_add_u32 s18, s18, 0xb0080
	v_lshl_add_u64 v[198:199], v[240:241], 0, s[22:23]
	s_addc_u32 s19, s19, 0
	s_add_i32 s60, s92, s68
	global_load_lds_dwordx4 v[198:199], off
	v_lshl_add_u64 v[198:199], s[18:19], 0, v[152:153]
	s_mov_b32 m0, s60
	s_nop 0
	global_load_lds_dwordx4 v[198:199], off
	v_lshl_add_u64 v[198:199], s[18:19], 0, v[172:173]
	s_add_i32 m0, s60, 0x2000
	s_nop 0
	global_load_lds_dwordx4 v[198:199], off
	v_lshl_add_u64 v[198:199], v[242:243], 0, s[22:23]
	s_mov_b32 m0, s79
	s_nop 0
	global_load_lds_dwordx4 v[198:199], off
	v_lshl_add_u64 v[198:199], v[244:245], 0, s[22:23]
	s_mov_b32 m0, s80
	s_nop 0
	global_load_lds_dwordx4 v[198:199], off
	s_waitcnt vmcnt(8)
	s_waitcnt lgkmcnt(0)
	s_barrier
	s_setprio 1
	s_waitcnt lgkmcnt(0)
	v_mfma_f32_16x16x32_bf16 v[60:63], v[128:131], v[190:193], v[60:63]
	v_mfma_f32_16x16x32_bf16 v[56:59], v[136:139], v[190:193], v[56:59]
	v_mfma_f32_16x16x32_bf16 v[44:47], v[128:131], v[214:217], v[44:47]
	v_mfma_f32_16x16x32_bf16 v[40:43], v[136:139], v[214:217], v[40:43]
	v_mfma_f32_16x16x32_bf16 v[28:31], v[128:131], v[224:227], v[28:31]
	v_mfma_f32_16x16x32_bf16 v[24:27], v[136:139], v[224:227], v[24:27]
	v_mfma_f32_16x16x32_bf16 v[12:15], v[128:131], v[232:235], v[12:15]
	v_mfma_f32_16x16x32_bf16 v[8:11], v[136:139], v[232:235], v[8:11]
	v_mfma_f32_16x16x32_bf16 v[60:63], v[132:135], v[194:197], v[60:63]
	v_mfma_f32_16x16x32_bf16 v[56:59], v[140:143], v[194:197], v[56:59]
	v_mfma_f32_16x16x32_bf16 v[44:47], v[132:135], v[218:221], v[44:47]
	v_mfma_f32_16x16x32_bf16 v[40:43], v[140:143], v[218:221], v[40:43]
	v_mfma_f32_16x16x32_bf16 v[28:31], v[132:135], v[228:231], v[28:31]
	v_mfma_f32_16x16x32_bf16 v[24:27], v[140:143], v[228:231], v[24:27]
	v_mfma_f32_16x16x32_bf16 v[12:15], v[132:135], v[236:239], v[12:15]
	v_mfma_f32_16x16x32_bf16 v[8:11], v[140:143], v[236:239], v[8:11]
	s_setprio 0
	s_setprio 1
	v_mfma_f32_16x16x32_bf16 v[52:55], v[144:147], v[190:193], v[52:55]
	v_mfma_f32_16x16x32_bf16 v[48:51], v[182:185], v[190:193], v[48:51]
	v_mfma_f32_16x16x32_bf16 v[36:39], v[144:147], v[214:217], v[36:39]
	v_mfma_f32_16x16x32_bf16 v[32:35], v[182:185], v[214:217], v[32:35]
	v_mfma_f32_16x16x32_bf16 v[20:23], v[144:147], v[224:227], v[20:23]
	v_mfma_f32_16x16x32_bf16 v[16:19], v[182:185], v[224:227], v[16:19]
	v_mfma_f32_16x16x32_bf16 v[4:7], v[144:147], v[232:235], v[4:7]
	v_mfma_f32_16x16x32_bf16 v[0:3], v[182:185], v[232:235], v[0:3]
	v_mfma_f32_16x16x32_bf16 v[52:55], v[148:151], v[194:197], v[52:55]
	v_mfma_f32_16x16x32_bf16 v[48:51], v[186:189], v[194:197], v[48:51]
	v_mfma_f32_16x16x32_bf16 v[36:39], v[148:151], v[218:221], v[36:39]
	v_mfma_f32_16x16x32_bf16 v[32:35], v[186:189], v[218:221], v[32:35]
	v_mfma_f32_16x16x32_bf16 v[20:23], v[148:151], v[228:231], v[20:23]
	v_mfma_f32_16x16x32_bf16 v[16:19], v[186:189], v[228:231], v[16:19]
	v_mfma_f32_16x16x32_bf16 v[4:7], v[148:151], v[236:239], v[4:7]
	v_mfma_f32_16x16x32_bf16 v[0:3], v[186:189], v[236:239], v[0:3]
	s_setprio 0
	s_barrier
	s_add_i32 s86, s86, 2
	s_add_u32 s84, s84, 0x100
	s_addc_u32 s85, s85, 0
	s_cmp_gt_u32 s86, 41
	s_mov_b64 s[60:61], vcc
	s_cbranch_scc0 .LBB0_281
	s_and_b64 vcc, exec, s[10:11]
	s_cbranch_vccz .LBB0_284
	s_barrier

.LBB0_419:
	s_add_u32 s44, s48, 0xfffc0080
	s_addc_u32 s45, s49, -1
	s_add_i32 s83, 0, 0x10000
	s_cmp_eq_u32 s82, 12
	s_cselect_b32 s63, s21, s45
	s_cselect_b32 s62, s78, s44
	s_cselect_b32 s45, s19, s81
	s_cselect_b32 s44, s79, s80
	s_add_i32 s86, 0, 0x14000
	v_add_u32_e32 v88, s83, v185
	v_add_u32_e32 v182, s86, v185
	ds_read_b128 v[72:75], v88
	ds_read_b128 v[76:79], v88 offset:1024
	ds_read_b128 v[80:83], v88 offset:2048
	ds_read_b128 v[88:91], v88 offset:3072
	ds_read_b128 v[174:177], v182
	ds_read_b128 v[178:181], v182 offset:1024
	ds_read_b128 v[190:193], v182 offset:2048
	ds_read_b128 v[194:197], v182 offset:3072
	v_lshl_add_u64 v[182:183], s[48:49], 0, v[172:173]
	s_add_i32 m0, s59, 0xc000
	ds_read_b128 v[210:213], v188
	ds_read_b128 v[214:217], v188 offset:1024
	ds_read_b128 v[218:221], v188 offset:2048
	ds_read_b128 v[224:227], v188 offset:3072
	ds_read_b128 v[228:231], v188 offset:4096
	ds_read_b128 v[232:235], v188 offset:5120
	ds_read_b128 v[236:239], v188 offset:6144
	ds_read_b128 v[240:243], v188 offset:7168
	global_load_lds_dwordx4 v[182:183], off
	v_lshl_add_u64 v[182:183], s[48:49], 0, v[150:151]
	s_add_i32 m0, s59, 0xe000
	s_nop 0
	global_load_lds_dwordx4 v[182:183], off
	s_waitcnt vmcnt(8)
	s_waitcnt lgkmcnt(0)
	s_barrier
	s_setprio 1
	s_waitcnt lgkmcnt(0)
	v_mfma_f32_16x16x32_bf16 v[140:143], v[72:75], v[210:213], v[140:143]
	v_mfma_f32_16x16x32_bf16 v[136:139], v[80:83], v[210:213], v[136:139]
	v_mfma_f32_16x16x32_bf16 v[124:127], v[72:75], v[218:221], v[124:127]
	v_mfma_f32_16x16x32_bf16 v[120:123], v[80:83], v[218:221], v[120:123]
	v_mfma_f32_16x16x32_bf16 v[108:111], v[72:75], v[228:231], v[108:111]
	v_mfma_f32_16x16x32_bf16 v[104:107], v[80:83], v[228:231], v[104:107]
	v_mfma_f32_16x16x32_bf16 v[92:95], v[72:75], v[236:239], v[92:95]
	v_mfma_f32_16x16x32_bf16 v[84:87], v[80:83], v[236:239], v[84:87]
	v_mfma_f32_16x16x32_bf16 v[140:143], v[76:79], v[214:217], v[140:143]
	v_mfma_f32_16x16x32_bf16 v[136:139], v[88:91], v[214:217], v[136:139]
	v_mfma_f32_16x16x32_bf16 v[124:127], v[76:79], v[224:227], v[124:127]
	v_mfma_f32_16x16x32_bf16 v[120:123], v[88:91], v[224:227], v[120:123]
	v_mfma_f32_16x16x32_bf16 v[108:111], v[76:79], v[232:235], v[108:111]
	v_mfma_f32_16x16x32_bf16 v[104:107], v[88:91], v[232:235], v[104:107]
	v_mfma_f32_16x16x32_bf16 v[92:95], v[76:79], v[240:243], v[92:95]
	v_mfma_f32_16x16x32_bf16 v[84:87], v[88:91], v[240:243], v[84:87]
	s_setprio 0
	s_setprio 1
	v_mfma_f32_16x16x32_bf16 v[132:135], v[174:177], v[210:213], v[132:135]
	v_mfma_f32_16x16x32_bf16 v[128:131], v[190:193], v[210:213], v[128:131]
	v_mfma_f32_16x16x32_bf16 v[116:119], v[174:177], v[218:221], v[116:119]
	v_mfma_f32_16x16x32_bf16 v[112:115], v[190:193], v[218:221], v[112:115]
	v_mfma_f32_16x16x32_bf16 v[100:103], v[174:177], v[228:231], v[100:103]
	v_mfma_f32_16x16x32_bf16 v[96:99], v[190:193], v[228:231], v[96:99]
	v_mfma_f32_16x16x32_bf16 v[68:71], v[174:177], v[236:239], v[68:71]
	v_mfma_f32_16x16x32_bf16 v[64:67], v[190:193], v[236:239], v[64:67]
	v_mfma_f32_16x16x32_bf16 v[132:135], v[178:181], v[214:217], v[132:135]
	v_mfma_f32_16x16x32_bf16 v[128:131], v[194:197], v[214:217], v[128:131]
	v_mfma_f32_16x16x32_bf16 v[116:119], v[178:181], v[224:227], v[116:119]
	v_mfma_f32_16x16x32_bf16 v[112:115], v[194:197], v[224:227], v[112:115]
	v_mfma_f32_16x16x32_bf16 v[100:103], v[178:181], v[232:235], v[100:103]
	v_mfma_f32_16x16x32_bf16 v[96:99], v[194:197], v[232:235], v[96:99]
	v_mfma_f32_16x16x32_bf16 v[68:71], v[178:181], v[240:243], v[68:71]
	v_mfma_f32_16x16x32_bf16 v[64:67], v[194:197], v[240:243], v[64:67]
	s_setprio 0
	s_barrier
	s_add_i32 s83, s83, s8
	v_lshl_add_u64 v[182:183], s[44:45], 0, v[152:153]
	s_mov_b32 m0, s83
	ds_read_b128 v[210:213], v188 offset:16384
	ds_read_b128 v[214:217], v188 offset:17408
	ds_read_b128 v[218:221], v188 offset:18432
	ds_read_b128 v[224:227], v188 offset:19456
	ds_read_b128 v[228:231], v188 offset:20480
	ds_read_b128 v[232:235], v188 offset:21504
	ds_read_b128 v[236:239], v188 offset:22528
	ds_read_b128 v[240:243], v188 offset:23552
	global_load_lds_dwordx4 v[182:183], off
	s_add_i32 m0, s83, 0x2000
	s_add_u32 s84, s44, 0x40000
	v_lshl_add_u64 v[198:199], s[44:45], 0, v[144:145]
	s_addc_u32 s85, s45, 0
	s_add_i32 s83, s86, s8
	global_load_lds_dwordx4 v[198:199], off
	v_lshl_add_u64 v[244:245], s[84:85], 0, v[152:153]
	s_mov_b32 m0, s83
	v_lshl_add_u64 v[246:247], s[62:63], 0, v[146:147]
	global_load_lds_dwordx4 v[244:245], off
	v_lshl_add_u64 v[244:245], s[84:85], 0, v[144:145]
	s_add_i32 m0, s83, 0x2000
	s_nop 0
	global_load_lds_dwordx4 v[244:245], off
	v_lshl_add_u64 v[244:245], s[62:63], 0, v[148:149]
	s_mov_b32 m0, s59
	s_nop 0
	global_load_lds_dwordx4 v[244:245], off
	s_mov_b32 m0, s66
	s_nop 0
	global_load_lds_dwordx4 v[246:247], off
	s_waitcnt vmcnt(8)
	s_waitcnt lgkmcnt(0)
	s_barrier
	s_setprio 1
	s_waitcnt lgkmcnt(0)
	v_mfma_f32_16x16x32_bf16 v[60:63], v[72:75], v[210:213], v[60:63]
	v_mfma_f32_16x16x32_bf16 v[56:59], v[80:83], v[210:213], v[56:59]
	v_mfma_f32_16x16x32_bf16 v[44:47], v[72:75], v[218:221], v[44:47]
	v_mfma_f32_16x16x32_bf16 v[40:43], v[80:83], v[218:221], v[40:43]
	v_mfma_f32_16x16x32_bf16 v[28:31], v[72:75], v[228:231], v[28:31]
	v_mfma_f32_16x16x32_bf16 v[24:27], v[80:83], v[228:231], v[24:27]
	v_mfma_f32_16x16x32_bf16 v[12:15], v[72:75], v[236:239], v[12:15]
	v_mfma_f32_16x16x32_bf16 v[8:11], v[80:83], v[236:239], v[8:11]
	v_mfma_f32_16x16x32_bf16 v[60:63], v[76:79], v[214:217], v[60:63]
	v_mfma_f32_16x16x32_bf16 v[56:59], v[88:91], v[214:217], v[56:59]
	v_mfma_f32_16x16x32_bf16 v[44:47], v[76:79], v[224:227], v[44:47]
	v_mfma_f32_16x16x32_bf16 v[40:43], v[88:91], v[224:227], v[40:43]
	v_mfma_f32_16x16x32_bf16 v[28:31], v[76:79], v[232:235], v[28:31]
	v_mfma_f32_16x16x32_bf16 v[24:27], v[88:91], v[232:235], v[24:27]
	v_mfma_f32_16x16x32_bf16 v[12:15], v[76:79], v[240:243], v[12:15]
	v_mfma_f32_16x16x32_bf16 v[8:11], v[88:91], v[240:243], v[8:11]
	s_setprio 0
	s_setprio 1
	v_mfma_f32_16x16x32_bf16 v[52:55], v[174:177], v[210:213], v[52:55]
	v_mfma_f32_16x16x32_bf16 v[48:51], v[190:193], v[210:213], v[48:51]
	v_mfma_f32_16x16x32_bf16 v[36:39], v[174:177], v[218:221], v[36:39]
	v_mfma_f32_16x16x32_bf16 v[32:35], v[190:193], v[218:221], v[32:35]
	v_mfma_f32_16x16x32_bf16 v[20:23], v[174:177], v[228:231], v[20:23]
	v_mfma_f32_16x16x32_bf16 v[16:19], v[190:193], v[228:231], v[16:19]
	v_mfma_f32_16x16x32_bf16 v[4:7], v[174:177], v[236:239], v[4:7]
	v_mfma_f32_16x16x32_bf16 v[0:3], v[190:193], v[236:239], v[0:3]
	v_mfma_f32_16x16x32_bf16 v[52:55], v[178:181], v[214:217], v[52:55]
	v_mfma_f32_16x16x32_bf16 v[48:51], v[194:197], v[214:217], v[48:51]
	v_mfma_f32_16x16x32_bf16 v[36:39], v[178:181], v[224:227], v[36:39]
	v_mfma_f32_16x16x32_bf16 v[32:35], v[194:197], v[224:227], v[32:35]
	v_mfma_f32_16x16x32_bf16 v[20:23], v[178:181], v[232:235], v[20:23]
	v_mfma_f32_16x16x32_bf16 v[16:19], v[194:197], v[232:235], v[16:19]
	v_mfma_f32_16x16x32_bf16 v[4:7], v[178:181], v[240:243], v[4:7]
	v_mfma_f32_16x16x32_bf16 v[0:3], v[194:197], v[240:243], v[0:3]
	s_setprio 0
	s_barrier
	s_add_i32 s83, 0, 0x18000
	s_add_i32 s84, 0, 0x1c000
	v_add_u32_e32 v88, s83, v185
	v_add_u32_e32 v189, s84, v185
	ds_read_b128 v[72:75], v88
	ds_read_b128 v[76:79], v88 offset:1024
	ds_read_b128 v[80:83], v88 offset:2048
	ds_read_b128 v[88:91], v88 offset:3072
	ds_read_b128 v[174:177], v189
	ds_read_b128 v[178:181], v189 offset:1024
	ds_read_b128 v[190:193], v189 offset:2048
	ds_read_b128 v[194:197], v189 offset:3072
	s_add_u32 s62, s62, 0x40000
	s_addc_u32 s63, s63, 0
	s_mov_b32 m0, s67
	v_lshl_add_u64 v[248:249], s[62:63], 0, v[148:149]
	ds_read_b128 v[210:213], v188 offset:32768
	ds_read_b128 v[214:217], v188 offset:33792
	ds_read_b128 v[218:221], v188 offset:34816
	ds_read_b128 v[224:227], v188 offset:35840
	ds_read_b128 v[228:231], v188 offset:36864
	ds_read_b128 v[232:235], v188 offset:37888
	ds_read_b128 v[236:239], v188 offset:38912
	ds_read_b128 v[240:243], v188 offset:39936
	global_load_lds_dwordx4 v[248:249], off
	v_lshl_add_u64 v[248:249], s[62:63], 0, v[146:147]
	s_mov_b32 m0, s68
	s_nop 0
	global_load_lds_dwordx4 v[248:249], off
	s_waitcnt vmcnt(8)
	s_waitcnt lgkmcnt(0)
	s_barrier
	s_setprio 1
	s_waitcnt lgkmcnt(0)
	v_mfma_f32_16x16x32_bf16 v[140:143], v[72:75], v[210:213], v[140:143]
	v_mfma_f32_16x16x32_bf16 v[136:139], v[80:83], v[210:213], v[136:139]
	v_mfma_f32_16x16x32_bf16 v[124:127], v[72:75], v[218:221], v[124:127]
	v_mfma_f32_16x16x32_bf16 v[120:123], v[80:83], v[218:221], v[120:123]
	v_mfma_f32_16x16x32_bf16 v[108:111], v[72:75], v[228:231], v[108:111]
	v_mfma_f32_16x16x32_bf16 v[104:107], v[80:83], v[228:231], v[104:107]
	v_mfma_f32_16x16x32_bf16 v[92:95], v[72:75], v[236:239], v[92:95]
	v_mfma_f32_16x16x32_bf16 v[84:87], v[80:83], v[236:239], v[84:87]
	v_mfma_f32_16x16x32_bf16 v[140:143], v[76:79], v[214:217], v[140:143]
	v_mfma_f32_16x16x32_bf16 v[136:139], v[88:91], v[214:217], v[136:139]
	v_mfma_f32_16x16x32_bf16 v[124:127], v[76:79], v[224:227], v[124:127]
	v_mfma_f32_16x16x32_bf16 v[120:123], v[88:91], v[224:227], v[120:123]
	v_mfma_f32_16x16x32_bf16 v[108:111], v[76:79], v[232:235], v[108:111]
	v_mfma_f32_16x16x32_bf16 v[104:107], v[88:91], v[232:235], v[104:107]
	v_mfma_f32_16x16x32_bf16 v[92:95], v[76:79], v[240:243], v[92:95]
	v_mfma_f32_16x16x32_bf16 v[84:87], v[88:91], v[240:243], v[84:87]
	s_setprio 0
	s_setprio 1
	v_mfma_f32_16x16x32_bf16 v[132:135], v[174:177], v[210:213], v[132:135]
	v_mfma_f32_16x16x32_bf16 v[128:131], v[190:193], v[210:213], v[128:131]
	v_mfma_f32_16x16x32_bf16 v[116:119], v[174:177], v[218:221], v[116:119]
	v_mfma_f32_16x16x32_bf16 v[112:115], v[190:193], v[218:221], v[112:115]
	v_mfma_f32_16x16x32_bf16 v[100:103], v[174:177], v[228:231], v[100:103]
	v_mfma_f32_16x16x32_bf16 v[96:99], v[190:193], v[228:231], v[96:99]
	v_mfma_f32_16x16x32_bf16 v[68:71], v[174:177], v[236:239], v[68:71]
	v_mfma_f32_16x16x32_bf16 v[64:67], v[190:193], v[236:239], v[64:67]
	v_mfma_f32_16x16x32_bf16 v[132:135], v[178:181], v[214:217], v[132:135]
	v_mfma_f32_16x16x32_bf16 v[128:131], v[194:197], v[214:217], v[128:131]
	v_mfma_f32_16x16x32_bf16 v[116:119], v[178:181], v[224:227], v[116:119]
	v_mfma_f32_16x16x32_bf16 v[112:115], v[194:197], v[224:227], v[112:115]
	v_mfma_f32_16x16x32_bf16 v[100:103], v[178:181], v[232:235], v[100:103]
	v_mfma_f32_16x16x32_bf16 v[96:99], v[194:197], v[232:235], v[96:99]
	v_mfma_f32_16x16x32_bf16 v[68:71], v[178:181], v[240:243], v[68:71]
	v_mfma_f32_16x16x32_bf16 v[64:67], v[194:197], v[240:243], v[64:67]
	s_setprio 0
	s_barrier
	s_add_i32 s62, s83, s8
	v_lshl_add_u64 v[182:183], v[182:183], 0, s[22:23]
	s_mov_b32 m0, s62
	ds_read_b128 v[210:213], v188 offset:49152
	ds_read_b128 v[214:217], v188 offset:50176
	ds_read_b128 v[218:221], v188 offset:51200
	ds_read_b128 v[224:227], v188 offset:52224
	ds_read_b128 v[228:231], v188 offset:53248
	ds_read_b128 v[232:235], v188 offset:54272
	ds_read_b128 v[236:239], v188 offset:55296
	ds_read_b128 v[240:243], v188 offset:56320
	global_load_lds_dwordx4 v[182:183], off
	s_add_i32 m0, s62, 0x2000
	s_add_u32 s44, s44, 0x40080
	v_lshl_add_u64 v[182:183], v[198:199], 0, s[22:23]
	s_addc_u32 s45, s45, 0
	s_add_i32 s62, s84, s8
	global_load_lds_dwordx4 v[182:183], off
	v_lshl_add_u64 v[182:183], s[44:45], 0, v[152:153]
	s_mov_b32 m0, s62
	s_nop 0
	global_load_lds_dwordx4 v[182:183], off
	v_lshl_add_u64 v[182:183], s[44:45], 0, v[144:145]
	s_add_i32 m0, s62, 0x2000
	s_nop 0
	global_load_lds_dwordx4 v[182:183], off
	v_lshl_add_u64 v[182:183], v[244:245], 0, s[22:23]
	s_mov_b32 m0, s69
	s_nop 0
	global_load_lds_dwordx4 v[182:183], off
	v_lshl_add_u64 v[182:183], v[246:247], 0, s[22:23]
	s_mov_b32 m0, s74
	s_nop 0
	global_load_lds_dwordx4 v[182:183], off
	s_waitcnt vmcnt(8)
	s_waitcnt lgkmcnt(0)
	s_barrier
	s_setprio 1
	s_waitcnt lgkmcnt(0)
	v_mfma_f32_16x16x32_bf16 v[60:63], v[72:75], v[210:213], v[60:63]
	v_mfma_f32_16x16x32_bf16 v[56:59], v[80:83], v[210:213], v[56:59]
	v_mfma_f32_16x16x32_bf16 v[44:47], v[72:75], v[218:221], v[44:47]
	v_mfma_f32_16x16x32_bf16 v[40:43], v[80:83], v[218:221], v[40:43]
	v_mfma_f32_16x16x32_bf16 v[28:31], v[72:75], v[228:231], v[28:31]
	v_mfma_f32_16x16x32_bf16 v[24:27], v[80:83], v[228:231], v[24:27]
	v_mfma_f32_16x16x32_bf16 v[12:15], v[72:75], v[236:239], v[12:15]
	v_mfma_f32_16x16x32_bf16 v[8:11], v[80:83], v[236:239], v[8:11]
	v_mfma_f32_16x16x32_bf16 v[60:63], v[76:79], v[214:217], v[60:63]
	v_mfma_f32_16x16x32_bf16 v[56:59], v[88:91], v[214:217], v[56:59]
	v_mfma_f32_16x16x32_bf16 v[44:47], v[76:79], v[224:227], v[44:47]
	v_mfma_f32_16x16x32_bf16 v[40:43], v[88:91], v[224:227], v[40:43]
	v_mfma_f32_16x16x32_bf16 v[28:31], v[76:79], v[232:235], v[28:31]
	v_mfma_f32_16x16x32_bf16 v[24:27], v[88:91], v[232:235], v[24:27]
	v_mfma_f32_16x16x32_bf16 v[12:15], v[76:79], v[240:243], v[12:15]
	v_mfma_f32_16x16x32_bf16 v[8:11], v[88:91], v[240:243], v[8:11]
	s_setprio 0
	s_setprio 1
	v_mfma_f32_16x16x32_bf16 v[52:55], v[174:177], v[210:213], v[52:55]
	v_mfma_f32_16x16x32_bf16 v[48:51], v[190:193], v[210:213], v[48:51]
	v_mfma_f32_16x16x32_bf16 v[36:39], v[174:177], v[218:221], v[36:39]
	v_mfma_f32_16x16x32_bf16 v[32:35], v[190:193], v[218:221], v[32:35]
	v_mfma_f32_16x16x32_bf16 v[20:23], v[174:177], v[228:231], v[20:23]
	v_mfma_f32_16x16x32_bf16 v[16:19], v[190:193], v[228:231], v[16:19]
	v_mfma_f32_16x16x32_bf16 v[4:7], v[174:177], v[236:239], v[4:7]
	v_mfma_f32_16x16x32_bf16 v[0:3], v[190:193], v[236:239], v[0:3]
	v_mfma_f32_16x16x32_bf16 v[52:55], v[178:181], v[214:217], v[52:55]
	v_mfma_f32_16x16x32_bf16 v[48:51], v[194:197], v[214:217], v[48:51]
	v_mfma_f32_16x16x32_bf16 v[36:39], v[178:181], v[224:227], v[36:39]
	v_mfma_f32_16x16x32_bf16 v[32:35], v[194:197], v[224:227], v[32:35]
	v_mfma_f32_16x16x32_bf16 v[20:23], v[178:181], v[232:235], v[20:23]
	v_mfma_f32_16x16x32_bf16 v[16:19], v[194:197], v[232:235], v[16:19]
	v_mfma_f32_16x16x32_bf16 v[4:7], v[178:181], v[240:243], v[4:7]
	v_mfma_f32_16x16x32_bf16 v[0:3], v[194:197], v[240:243], v[0:3]
	s_setprio 0
	s_barrier
	s_add_i32 s82, s82, 2
	s_add_u32 s80, s80, 0x100
	s_addc_u32 s81, s81, 0
	s_add_u32 s48, s48, 0x100
	s_addc_u32 s49, s49, 0
	s_cmp_gt_u32 s82, 13
	s_cbranch_scc0 .LBB0_419
	s_and_b64 vcc, exec, s[16:17]
	s_cbranch_vccz .LBB0_422
	s_barrier

.LBB0_565:
	s_and_b32 s60, s45, 1
	s_bfe_u32 s59, s45, 0x60001
	s_ashr_i32 s0, s45, 7
	s_lshl_b32 s1, s60, 2
	s_lshl_b32 s50, s59, 7
	s_add_i32 s16, s1, s20
	s_ashr_i32 s1, s0, 31
	s_add_i32 s51, s50, 0xffffff80
	s_lshl_b64 s[18:19], s[0:1], 13
	v_or_b32_e32 v0, s50, v112
	v_add_u32_e32 v6, s51, v119
	v_or_b32_e32 v0, s18, v0
	v_mov_b64_e32 v[4:5], s[56:57]
	v_cmp_gt_u32_e32 vcc, s37, v6
	v_mad_u64_u32 v[0:1], s[66:67], v0, s53, v[4:5]
	s_lshl_b32 s18, s16, 6
	s_lshl_b32 s17, s0, 13
	v_cndmask_b32_e32 v28, 0, v6, vcc
	v_mad_i32_i24 v1, s19, v207, v1
	s_ashr_i32 s19, s18, 31
	v_add_u32_e32 v6, s17, v28
	v_lshl_add_u64 v[0:1], s[18:19], 1, v[0:1]
	v_lshlrev_b32_e32 v152, 1, v84
	v_mad_i64_i32 v[4:5], s[18:19], v6, s53, v[4:5]
	s_lshl_b32 s8, s60, 7
	v_lshl_add_u64 v[106:107], v[0:1], 0, v[152:153]
	v_lshl_add_u64 v[4:5], v[4:5], 0, s[8:9]
	v_lshlrev_b32_e32 v152, 1, v86
	v_lshl_add_u64 v[4:5], v[4:5], 0, v[152:153]
	global_load_dwordx4 v[0:3], v[106:107], off
	global_load_dwordx4 v[8:11], v[106:107], off offset:64
	v_add_u32_e32 v12, s51, v119
	v_cmp_gt_u32_e32 vcc, s37, v12
	s_nop 1
	v_cndmask_b32_e32 v29, 0, v12, vcc
	v_add_u32_e32 v12, s17, v29
	v_mov_b64_e32 v[14:15], s[56:57]
	v_mad_i64_i32 v[14:15], s[18:19], v12, s53, v[14:15]
	v_lshl_add_u64 v[14:15], v[14:15], 0, s[8:9]
	v_lshl_add_u64 v[14:15], v[14:15], 0, v[152:153]
	global_load_dwordx4 v[44:47], v[14:15], off offset:1024
	v_add_u32_e32 v12, s51, v120
	v_cmp_gt_u32_e32 vcc, s37, v12
	s_nop 1
	v_cndmask_b32_e32 v29, 0, v12, vcc
	v_add_u32_e32 v12, s17, v29
	v_mov_b64_e32 v[14:15], s[56:57]
	v_mad_i64_i32 v[14:15], s[18:19], v12, s53, v[14:15]
	v_lshl_add_u64 v[14:15], v[14:15], 0, s[8:9]
	v_lshl_add_u64 v[14:15], v[14:15], 0, v[152:153]
	global_load_dwordx4 v[48:51], v[14:15], off offset:1024
	v_add_u32_e32 v12, s51, v121
	v_cmp_gt_u32_e32 vcc, s37, v12
	s_nop 1
	v_cndmask_b32_e32 v29, 0, v12, vcc
	v_add_u32_e32 v12, s17, v29
	v_mov_b64_e32 v[14:15], s[56:57]
	v_mad_i64_i32 v[14:15], s[18:19], v12, s53, v[14:15]
	v_lshl_add_u64 v[14:15], v[14:15], 0, s[8:9]
	v_lshl_add_u64 v[14:15], v[14:15], 0, v[152:153]
	global_load_dwordx4 v[52:55], v[14:15], off offset:1024
	v_add_u32_e32 v12, s51, v122
	v_cmp_gt_u32_e32 vcc, s37, v12
	s_nop 1
	v_cndmask_b32_e32 v29, 0, v12, vcc
	v_add_u32_e32 v12, s17, v29
	v_mov_b64_e32 v[14:15], s[56:57]
	v_mad_i64_i32 v[14:15], s[18:19], v12, s53, v[14:15]
	v_lshl_add_u64 v[14:15], v[14:15], 0, s[8:9]
	v_lshl_add_u64 v[14:15], v[14:15], 0, v[152:153]
	global_load_dwordx4 v[56:59], v[14:15], off offset:1024
	v_add_u32_e32 v12, s51, v123
	v_cmp_gt_u32_e32 vcc, s37, v12
	s_nop 1
	v_cndmask_b32_e32 v29, 0, v12, vcc
	v_add_u32_e32 v12, s17, v29
	v_mov_b64_e32 v[14:15], s[56:57]
	v_mad_i64_i32 v[14:15], s[18:19], v12, s53, v[14:15]
	v_lshl_add_u64 v[14:15], v[14:15], 0, s[8:9]
	v_lshl_add_u64 v[14:15], v[14:15], 0, v[152:153]
	global_load_dwordx4 v[60:63], v[14:15], off offset:1024
	v_add_u32_e32 v12, s51, v124
	v_cmp_gt_u32_e32 vcc, s37, v12
	s_nop 1
	v_cndmask_b32_e32 v29, 0, v12, vcc
	v_add_u32_e32 v12, s17, v29
	v_mov_b64_e32 v[14:15], s[56:57]
	v_mad_i64_i32 v[14:15], s[18:19], v12, s53, v[14:15]
	v_lshl_add_u64 v[14:15], v[14:15], 0, s[8:9]
	v_lshl_add_u64 v[14:15], v[14:15], 0, v[152:153]
	global_load_dwordx4 v[64:67], v[14:15], off offset:1024
	s_and_saveexec_b64 s[18:19], s[46:47]
	v_add_u32_e32 v12, s51, v119
	v_cmp_gt_u32_e32 vcc, s37, v12
	s_nop 1
	v_cndmask_b32_e32 v29, 0, v12, vcc
	v_lshlrev_b32_e32 v12, 4, v29
	v_ashrrev_i32_e32 v13, 31, v12
	v_lshl_add_u64 v[16:17], v[12:13], 2, s[12:13]
	global_load_dwordx4 v[68:71], v[16:17], off
	global_load_dwordx4 v[72:75], v[16:17], off offset:16
	global_load_dwordx4 v[76:79], v[16:17], off offset:32
	global_load_dwordx4 v[80:83], v[16:17], off offset:48
	v_add_u32_e32 v12, s51, v120
	v_cmp_gt_u32_e32 vcc, s37, v12
	s_nop 1
	v_cndmask_b32_e32 v29, 0, v12, vcc
	v_lshlrev_b32_e32 v12, 4, v29
	v_ashrrev_i32_e32 v13, 31, v12
	v_lshl_add_u64 v[16:17], v[12:13], 2, s[12:13]
	global_load_dwordx4 v[176:179], v[16:17], off
	global_load_dwordx4 v[180:183], v[16:17], off offset:16
	global_load_dwordx4 v[184:187], v[16:17], off offset:32
	global_load_dwordx4 v[188:191], v[16:17], off offset:48
	v_add_u32_e32 v12, s51, v121
	v_cmp_gt_u32_e32 vcc, s37, v12
	s_nop 1
	v_cndmask_b32_e32 v29, 0, v12, vcc
	v_lshlrev_b32_e32 v12, 4, v29
	v_ashrrev_i32_e32 v13, 31, v12
	v_lshl_add_u64 v[16:17], v[12:13], 2, s[12:13]
	global_load_dwordx4 v[192:195], v[16:17], off
	global_load_dwordx4 v[196:199], v[16:17], off offset:16
	global_load_dwordx4 v[144:147], v[16:17], off offset:32
	global_load_dwordx4 v[148:151], v[16:17], off offset:48
	v_add_u32_e32 v12, s51, v122
	v_cmp_gt_u32_e32 vcc, s37, v12
	s_nop 1
	v_cndmask_b32_e32 v29, 0, v12, vcc
	v_lshlrev_b32_e32 v12, 4, v29
	v_ashrrev_i32_e32 v13, 31, v12
	v_lshl_add_u64 v[16:17], v[12:13], 2, s[12:13]
	global_load_dwordx4 v[210:213], v[16:17], off
	global_load_dwordx4 v[214:217], v[16:17], off offset:16
	global_load_dwordx4 v[218:221], v[16:17], off offset:32
	global_load_dwordx4 v[224:227], v[16:17], off offset:48
	v_add_u32_e32 v12, s51, v123
	v_cmp_gt_u32_e32 vcc, s37, v12
	s_nop 1
	v_cndmask_b32_e32 v29, 0, v12, vcc
	v_lshlrev_b32_e32 v12, 4, v29
	v_ashrrev_i32_e32 v13, 31, v12
	v_lshl_add_u64 v[16:17], v[12:13], 2, s[12:13]
	global_load_dwordx4 v[228:231], v[16:17], off
	global_load_dwordx4 v[232:235], v[16:17], off offset:16
	global_load_dwordx4 v[236:239], v[16:17], off offset:32
	global_load_dwordx4 v[172:175], v[16:17], off offset:48
	s_or_b64 exec, exec, s[18:19]
	s_barrier
	s_waitcnt vmcnt(16)
	v_add_u32_e32 v12, s51, v119
	v_cmp_gt_u32_e32 vcc, s37, v12
	s_nop 1
	v_cndmask_b32_e32 v7, 0, v47, vcc
	v_cndmask_b32_e32 v6, 0, v46, vcc
	v_cndmask_b32_e32 v5, 0, v45, vcc
	v_cndmask_b32_e32 v4, 0, v44, vcc
	v_lshlrev_b32_e32 v13, 16, v5
	v_lshlrev_b32_e32 v12, 16, v4
	v_and_b32_e32 v15, 0xffff0000, v5
	v_and_b32_e32 v14, 0xffff0000, v4
	v_and_b32_e32 v17, 0xffff0000, v6
	v_lshlrev_b32_e32 v16, 16, v6
	v_and_b32_e32 v19, 0xffff0000, v7
	v_lshlrev_b32_e32 v18, 16, v7
	ds_bpermute_b32 v26, v113, v12
	ds_bpermute_b32 v24, v113, v14
	ds_bpermute_b32 v27, v113, v13
	ds_bpermute_b32 v25, v113, v15
	ds_bpermute_b32 v22, v113, v16
	ds_bpermute_b32 v23, v113, v17
	ds_bpermute_b32 v20, v113, v18
	ds_bpermute_b32 v21, v113, v19
	s_and_saveexec_b64 s[18:19], s[46:47]
	s_waitcnt lgkmcnt(4)
	v_pk_mul_f32 v[24:25], v[88:89], v[24:25]
	s_waitcnt lgkmcnt(2)
	v_pk_mul_f32 v[22:23], v[88:89], v[22:23]
	s_waitcnt lgkmcnt(0)
	v_pk_mul_f32 v[20:21], v[88:89], v[20:21]
	v_pk_mul_f32 v[26:27], v[88:89], v[26:27]
	v_mov_b32_e32 v40, v68
	v_mov_b32_e32 v41, v70
	v_mov_b32_e32 v42, v76
	v_mov_b32_e32 v43, v78
	v_mov_b32_e32 v30, v77
	v_mov_b32_e32 v31, v79
	v_mov_b32_e32 v6, v69
	v_mov_b32_e32 v7, v71
	v_pk_mul_f32 v[4:5], v[22:23], v[80:81]
	v_pk_mul_f32 v[20:21], v[20:21], v[82:83]
	v_pk_mul_f32 v[24:25], v[24:25], v[30:31]
	v_pk_mul_f32 v[22:23], v[26:27], v[42:43]
	v_pk_fma_f32 v[4:5], v[72:73], v[16:17], v[4:5]
	v_pk_fma_f32 v[16:17], v[74:75], v[18:19], v[20:21]
	v_pk_fma_f32 v[6:7], v[6:7], v[14:15], v[24:25]
	v_pk_fma_f32 v[12:13], v[40:41], v[12:13], v[22:23]
	v_and_b32_sdwa v15, v4, v203 dst_sel:DWORD dst_unused:UNUSED_PAD src0_sel:WORD_1 src1_sel:DWORD
	v_and_b32_sdwa v19, v16, v203 dst_sel:DWORD dst_unused:UNUSED_PAD src0_sel:WORD_1 src1_sel:DWORD
	v_and_b32_sdwa v22, v7, v203 dst_sel:DWORD dst_unused:UNUSED_PAD src0_sel:WORD_1 src1_sel:DWORD
	v_and_b32_sdwa v23, v6, v203 dst_sel:DWORD dst_unused:UNUSED_PAD src0_sel:WORD_1 src1_sel:DWORD
	v_and_b32_sdwa v14, v5, v203 dst_sel:DWORD dst_unused:UNUSED_PAD src0_sel:WORD_1 src1_sel:DWORD
	v_and_b32_sdwa v18, v17, v203 dst_sel:DWORD dst_unused:UNUSED_PAD src0_sel:WORD_1 src1_sel:DWORD
	v_and_b32_sdwa v20, v13, v203 dst_sel:DWORD dst_unused:UNUSED_PAD src0_sel:WORD_1 src1_sel:DWORD
	v_and_b32_sdwa v21, v12, v203 dst_sel:DWORD dst_unused:UNUSED_PAD src0_sel:WORD_1 src1_sel:DWORD
	v_add3_u32 v4, v4, v15, s54
	v_add3_u32 v15, v16, v19, s54
	v_add3_u32 v7, v7, v22, s54
	v_add3_u32 v6, v6, v23, s54
	v_add3_u32 v5, v5, v14, s54
	v_add3_u32 v14, v17, v18, s54
	v_add3_u32 v12, v12, v21, s54
	v_add3_u32 v13, v13, v20, s54
	v_lshrrev_b32_e32 v4, 16, v4
	v_lshrrev_b32_e32 v15, 16, v15
	v_and_b32_e32 v7, 0xffff0000, v7
	v_and_b32_e32 v16, 0xffff0000, v6
	v_and_or_b32 v6, v5, s52, v4
	v_or_b32_sdwa v5, v7, v13 dst_sel:DWORD dst_unused:UNUSED_PAD src0_sel:DWORD src1_sel:WORD_1
	v_or_b32_sdwa v4, v16, v12 dst_sel:DWORD dst_unused:UNUSED_PAD src0_sel:DWORD src1_sel:WORD_1
	v_and_or_b32 v7, v14, s52, v15
	s_or_b64 exec, exec, s[18:19]
	ds_write_b128 v85, v[4:7]
	s_and_saveexec_b64 s[18:19], s[46:47]
	v_add_u32_e32 v12, s51, v124
	v_cmp_gt_u32_e32 vcc, s37, v12
	s_nop 1
	v_cndmask_b32_e32 v29, 0, v12, vcc
	v_lshlrev_b32_e32 v12, 4, v29
	v_ashrrev_i32_e32 v13, 31, v12
	v_lshl_add_u64 v[16:17], v[12:13], 2, s[12:13]
	global_load_dwordx4 v[68:71], v[16:17], off
	global_load_dwordx4 v[72:75], v[16:17], off offset:16
	global_load_dwordx4 v[76:79], v[16:17], off offset:32
	global_load_dwordx4 v[80:83], v[16:17], off offset:48
	s_or_b64 exec, exec, s[18:19]
	s_waitcnt vmcnt(16)
	v_add_u32_e32 v12, s51, v120
	v_cmp_gt_u32_e32 vcc, s37, v12
	s_nop 1
	v_cndmask_b32_e32 v7, 0, v51, vcc
	v_cndmask_b32_e32 v6, 0, v50, vcc
	v_cndmask_b32_e32 v5, 0, v49, vcc
	v_cndmask_b32_e32 v4, 0, v48, vcc
	v_lshlrev_b32_e32 v13, 16, v5
	v_lshlrev_b32_e32 v12, 16, v4
	v_and_b32_e32 v15, 0xffff0000, v5
	v_and_b32_e32 v14, 0xffff0000, v4
	v_and_b32_e32 v17, 0xffff0000, v6
	v_lshlrev_b32_e32 v16, 16, v6
	v_and_b32_e32 v19, 0xffff0000, v7
	v_lshlrev_b32_e32 v18, 16, v7
	ds_bpermute_b32 v26, v113, v12
	ds_bpermute_b32 v24, v113, v14
	ds_bpermute_b32 v27, v113, v13
	ds_bpermute_b32 v25, v113, v15
	ds_bpermute_b32 v22, v113, v16
	ds_bpermute_b32 v23, v113, v17
	ds_bpermute_b32 v20, v113, v18
	ds_bpermute_b32 v21, v113, v19
	s_and_saveexec_b64 s[18:19], s[46:47]
	s_waitcnt lgkmcnt(4)
	v_pk_mul_f32 v[24:25], v[88:89], v[24:25]
	s_waitcnt lgkmcnt(2)
	v_pk_mul_f32 v[22:23], v[88:89], v[22:23]
	s_waitcnt lgkmcnt(0)
	v_pk_mul_f32 v[20:21], v[88:89], v[20:21]
	v_pk_mul_f32 v[26:27], v[88:89], v[26:27]
	v_mov_b32_e32 v40, v176
	v_mov_b32_e32 v41, v178
	v_mov_b32_e32 v42, v184
	v_mov_b32_e32 v43, v186
	v_mov_b32_e32 v30, v185
	v_mov_b32_e32 v31, v187
	v_mov_b32_e32 v6, v177
	v_mov_b32_e32 v7, v179
	v_pk_mul_f32 v[4:5], v[22:23], v[188:189]
	v_pk_mul_f32 v[20:21], v[20:21], v[190:191]
	v_pk_mul_f32 v[24:25], v[24:25], v[30:31]
	v_pk_mul_f32 v[22:23], v[26:27], v[42:43]
	v_pk_fma_f32 v[4:5], v[180:181], v[16:17], v[4:5]
	v_pk_fma_f32 v[16:17], v[182:183], v[18:19], v[20:21]
	v_pk_fma_f32 v[6:7], v[6:7], v[14:15], v[24:25]
	v_pk_fma_f32 v[12:13], v[40:41], v[12:13], v[22:23]
	v_and_b32_sdwa v15, v4, v203 dst_sel:DWORD dst_unused:UNUSED_PAD src0_sel:WORD_1 src1_sel:DWORD
	v_and_b32_sdwa v19, v16, v203 dst_sel:DWORD dst_unused:UNUSED_PAD src0_sel:WORD_1 src1_sel:DWORD
	v_and_b32_sdwa v22, v7, v203 dst_sel:DWORD dst_unused:UNUSED_PAD src0_sel:WORD_1 src1_sel:DWORD
	v_and_b32_sdwa v23, v6, v203 dst_sel:DWORD dst_unused:UNUSED_PAD src0_sel:WORD_1 src1_sel:DWORD
	v_and_b32_sdwa v14, v5, v203 dst_sel:DWORD dst_unused:UNUSED_PAD src0_sel:WORD_1 src1_sel:DWORD
	v_and_b32_sdwa v18, v17, v203 dst_sel:DWORD dst_unused:UNUSED_PAD src0_sel:WORD_1 src1_sel:DWORD
	v_and_b32_sdwa v20, v13, v203 dst_sel:DWORD dst_unused:UNUSED_PAD src0_sel:WORD_1 src1_sel:DWORD
	v_and_b32_sdwa v21, v12, v203 dst_sel:DWORD dst_unused:UNUSED_PAD src0_sel:WORD_1 src1_sel:DWORD
	v_add3_u32 v4, v4, v15, s54
	v_add3_u32 v15, v16, v19, s54
	v_add3_u32 v7, v7, v22, s54
	v_add3_u32 v6, v6, v23, s54
	v_add3_u32 v5, v5, v14, s54
	v_add3_u32 v14, v17, v18, s54
	v_add3_u32 v12, v12, v21, s54
	v_add3_u32 v13, v13, v20, s54
	v_lshrrev_b32_e32 v4, 16, v4
	v_lshrrev_b32_e32 v15, 16, v15
	v_and_b32_e32 v7, 0xffff0000, v7
	v_and_b32_e32 v16, 0xffff0000, v6
	v_and_or_b32 v6, v5, s52, v4
	v_or_b32_sdwa v5, v7, v13 dst_sel:DWORD dst_unused:UNUSED_PAD src0_sel:DWORD src1_sel:WORD_1
	v_or_b32_sdwa v4, v16, v12 dst_sel:DWORD dst_unused:UNUSED_PAD src0_sel:DWORD src1_sel:WORD_1
	v_and_or_b32 v7, v14, s52, v15
	s_or_b64 exec, exec, s[18:19]
	ds_write_b128 v138, v[4:7]
	v_add_u32_e32 v12, s51, v125
	v_cmp_gt_u32_e32 vcc, s37, v12
	s_nop 1
	v_cndmask_b32_e32 v29, 0, v12, vcc
	v_add_u32_e32 v12, s17, v29
	v_mov_b64_e32 v[14:15], s[56:57]
	v_mad_i64_i32 v[14:15], s[18:19], v12, s53, v[14:15]
	v_lshl_add_u64 v[14:15], v[14:15], 0, s[8:9]
	v_lshl_add_u64 v[14:15], v[92:93], 1, v[14:15]
	global_load_dwordx4 v[44:47], v[14:15], off offset:1280
	v_add_u32_e32 v12, s51, v127
	v_cmp_gt_u32_e32 vcc, s37, v12
	s_nop 1
	v_cndmask_b32_e32 v29, 0, v12, vcc
	v_add_u32_e32 v12, s17, v29
	v_mov_b64_e32 v[14:15], s[56:57]
	v_mad_i64_i32 v[14:15], s[18:19], v12, s53, v[14:15]
	v_lshl_add_u64 v[14:15], v[14:15], 0, s[8:9]
	v_lshl_add_u64 v[14:15], v[94:95], 1, v[14:15]
	global_load_dwordx4 v[48:51], v[14:15], off offset:1280
	v_add_u32_e32 v12, s51, v129
	v_cmp_gt_u32_e32 vcc, s37, v12
	s_nop 1
	v_cndmask_b32_e32 v29, 0, v12, vcc
	v_add_u32_e32 v12, s17, v29
	v_mov_b64_e32 v[14:15], s[56:57]
	v_mad_i64_i32 v[14:15], s[18:19], v12, s53, v[14:15]
	v_lshl_add_u64 v[14:15], v[14:15], 0, s[8:9]
	v_lshl_add_u64 v[14:15], v[96:97], 1, v[14:15]
	global_load_dwordx4 v[176:179], v[14:15], off offset:1280
	v_add_u32_e32 v12, s51, v131
	v_cmp_gt_u32_e32 vcc, s37, v12
	s_nop 1
	v_cndmask_b32_e32 v29, 0, v12, vcc
	v_add_u32_e32 v12, s17, v29
	v_mov_b64_e32 v[14:15], s[56:57]
	v_mad_i64_i32 v[14:15], s[18:19], v12, s53, v[14:15]
	v_lshl_add_u64 v[14:15], v[14:15], 0, s[8:9]
	v_lshl_add_u64 v[14:15], v[98:99], 1, v[14:15]
	global_load_dwordx4 v[180:183], v[14:15], off offset:1280
	v_add_u32_e32 v12, s51, v133
	v_cmp_gt_u32_e32 vcc, s37, v12
	s_nop 1
	v_cndmask_b32_e32 v29, 0, v12, vcc
	v_add_u32_e32 v12, s17, v29
	v_mov_b64_e32 v[14:15], s[56:57]
	v_mad_i64_i32 v[14:15], s[18:19], v12, s53, v[14:15]
	v_lshl_add_u64 v[14:15], v[14:15], 0, s[8:9]
	v_lshl_add_u64 v[14:15], v[100:101], 1, v[14:15]
	global_load_dwordx4 v[184:187], v[14:15], off offset:1280
	v_add_u32_e32 v12, s51, v135
	v_cmp_gt_u32_e32 vcc, s37, v12
	s_nop 1
	v_cndmask_b32_e32 v29, 0, v12, vcc
	v_add_u32_e32 v12, s17, v29
	v_mov_b64_e32 v[14:15], s[56:57]
	v_mad_i64_i32 v[14:15], s[18:19], v12, s53, v[14:15]
	v_lshl_add_u64 v[14:15], v[14:15], 0, s[8:9]
	v_lshl_add_u64 v[14:15], v[102:103], 1, v[14:15]
	global_load_dwordx4 v[188:191], v[14:15], off offset:1280
	s_waitcnt vmcnt(18)
	v_add_u32_e32 v12, s51, v121
	v_cmp_gt_u32_e32 vcc, s37, v12
	s_nop 1
	v_cndmask_b32_e32 v7, 0, v55, vcc
	v_cndmask_b32_e32 v6, 0, v54, vcc
	v_cndmask_b32_e32 v5, 0, v53, vcc
	v_cndmask_b32_e32 v4, 0, v52, vcc
	v_lshlrev_b32_e32 v13, 16, v5
	v_lshlrev_b32_e32 v12, 16, v4
	v_and_b32_e32 v15, 0xffff0000, v5
	v_and_b32_e32 v14, 0xffff0000, v4
	v_and_b32_e32 v17, 0xffff0000, v6
	v_lshlrev_b32_e32 v16, 16, v6
	v_and_b32_e32 v19, 0xffff0000, v7
	v_lshlrev_b32_e32 v18, 16, v7
	ds_bpermute_b32 v26, v113, v12
	ds_bpermute_b32 v24, v113, v14
	ds_bpermute_b32 v27, v113, v13
	ds_bpermute_b32 v25, v113, v15
	ds_bpermute_b32 v22, v113, v16
	ds_bpermute_b32 v23, v113, v17
	ds_bpermute_b32 v20, v113, v18
	ds_bpermute_b32 v21, v113, v19
	s_and_saveexec_b64 s[18:19], s[46:47]
	s_waitcnt lgkmcnt(4)
	v_pk_mul_f32 v[24:25], v[88:89], v[24:25]
	s_waitcnt lgkmcnt(2)
	v_pk_mul_f32 v[22:23], v[88:89], v[22:23]
	s_waitcnt lgkmcnt(0)
	v_pk_mul_f32 v[20:21], v[88:89], v[20:21]
	v_pk_mul_f32 v[26:27], v[88:89], v[26:27]
	v_mov_b32_e32 v40, v192
	v_mov_b32_e32 v41, v194
	v_mov_b32_e32 v42, v144
	v_mov_b32_e32 v43, v146
	v_mov_b32_e32 v30, v145
	v_mov_b32_e32 v31, v147
	v_mov_b32_e32 v6, v193
	v_mov_b32_e32 v7, v195
	v_pk_mul_f32 v[4:5], v[22:23], v[148:149]
	v_pk_mul_f32 v[20:21], v[20:21], v[150:151]
	v_pk_mul_f32 v[24:25], v[24:25], v[30:31]
	v_pk_mul_f32 v[22:23], v[26:27], v[42:43]
	v_pk_fma_f32 v[4:5], v[196:197], v[16:17], v[4:5]
	v_pk_fma_f32 v[16:17], v[198:199], v[18:19], v[20:21]
	v_pk_fma_f32 v[6:7], v[6:7], v[14:15], v[24:25]
	v_pk_fma_f32 v[12:13], v[40:41], v[12:13], v[22:23]
	v_and_b32_sdwa v15, v4, v203 dst_sel:DWORD dst_unused:UNUSED_PAD src0_sel:WORD_1 src1_sel:DWORD
	v_and_b32_sdwa v19, v16, v203 dst_sel:DWORD dst_unused:UNUSED_PAD src0_sel:WORD_1 src1_sel:DWORD
	v_and_b32_sdwa v22, v7, v203 dst_sel:DWORD dst_unused:UNUSED_PAD src0_sel:WORD_1 src1_sel:DWORD
	v_and_b32_sdwa v23, v6, v203 dst_sel:DWORD dst_unused:UNUSED_PAD src0_sel:WORD_1 src1_sel:DWORD
	v_and_b32_sdwa v14, v5, v203 dst_sel:DWORD dst_unused:UNUSED_PAD src0_sel:WORD_1 src1_sel:DWORD
	v_and_b32_sdwa v18, v17, v203 dst_sel:DWORD dst_unused:UNUSED_PAD src0_sel:WORD_1 src1_sel:DWORD
	v_and_b32_sdwa v20, v13, v203 dst_sel:DWORD dst_unused:UNUSED_PAD src0_sel:WORD_1 src1_sel:DWORD
	v_and_b32_sdwa v21, v12, v203 dst_sel:DWORD dst_unused:UNUSED_PAD src0_sel:WORD_1 src1_sel:DWORD
	v_add3_u32 v4, v4, v15, s54
	v_add3_u32 v15, v16, v19, s54
	v_add3_u32 v7, v7, v22, s54
	v_add3_u32 v6, v6, v23, s54
	v_add3_u32 v5, v5, v14, s54
	v_add3_u32 v14, v17, v18, s54
	v_add3_u32 v12, v12, v21, s54
	v_add3_u32 v13, v13, v20, s54
	v_lshrrev_b32_e32 v4, 16, v4
	v_lshrrev_b32_e32 v15, 16, v15
	v_and_b32_e32 v7, 0xffff0000, v7
	v_and_b32_e32 v16, 0xffff0000, v6
	v_and_or_b32 v6, v5, s52, v4
	v_or_b32_sdwa v5, v7, v13 dst_sel:DWORD dst_unused:UNUSED_PAD src0_sel:DWORD src1_sel:WORD_1
	v_or_b32_sdwa v4, v16, v12 dst_sel:DWORD dst_unused:UNUSED_PAD src0_sel:DWORD src1_sel:WORD_1
	v_and_or_b32 v7, v14, s52, v15
	s_or_b64 exec, exec, s[18:19]
	ds_write_b128 v139, v[4:7]
	s_waitcnt vmcnt(14)
	v_add_u32_e32 v12, s51, v122
	v_cmp_gt_u32_e32 vcc, s37, v12
	s_nop 1
	v_cndmask_b32_e32 v7, 0, v59, vcc
	v_cndmask_b32_e32 v6, 0, v58, vcc
	v_cndmask_b32_e32 v5, 0, v57, vcc
	v_cndmask_b32_e32 v4, 0, v56, vcc
	v_lshlrev_b32_e32 v13, 16, v5
	v_lshlrev_b32_e32 v12, 16, v4
	v_and_b32_e32 v15, 0xffff0000, v5
	v_and_b32_e32 v14, 0xffff0000, v4
	v_and_b32_e32 v17, 0xffff0000, v6
	v_lshlrev_b32_e32 v16, 16, v6
	v_and_b32_e32 v19, 0xffff0000, v7
	v_lshlrev_b32_e32 v18, 16, v7
	ds_bpermute_b32 v26, v113, v12
	ds_bpermute_b32 v24, v113, v14
	ds_bpermute_b32 v27, v113, v13
	ds_bpermute_b32 v25, v113, v15
	ds_bpermute_b32 v22, v113, v16
	ds_bpermute_b32 v23, v113, v17
	ds_bpermute_b32 v20, v113, v18
	ds_bpermute_b32 v21, v113, v19
	s_and_saveexec_b64 s[18:19], s[46:47]
	s_waitcnt lgkmcnt(4)
	v_pk_mul_f32 v[24:25], v[88:89], v[24:25]
	s_waitcnt lgkmcnt(2)
	v_pk_mul_f32 v[22:23], v[88:89], v[22:23]
	s_waitcnt lgkmcnt(0)
	v_pk_mul_f32 v[20:21], v[88:89], v[20:21]
	v_pk_mul_f32 v[26:27], v[88:89], v[26:27]
	v_mov_b32_e32 v40, v210
	v_mov_b32_e32 v41, v212
	v_mov_b32_e32 v42, v218
	v_mov_b32_e32 v43, v220
	v_mov_b32_e32 v30, v219
	v_mov_b32_e32 v31, v221
	v_mov_b32_e32 v6, v211
	v_mov_b32_e32 v7, v213
	v_pk_mul_f32 v[4:5], v[22:23], v[224:225]
	v_pk_mul_f32 v[20:21], v[20:21], v[226:227]
	v_pk_mul_f32 v[24:25], v[24:25], v[30:31]
	v_pk_mul_f32 v[22:23], v[26:27], v[42:43]
	v_pk_fma_f32 v[4:5], v[214:215], v[16:17], v[4:5]
	v_pk_fma_f32 v[16:17], v[216:217], v[18:19], v[20:21]
	v_pk_fma_f32 v[6:7], v[6:7], v[14:15], v[24:25]
	v_pk_fma_f32 v[12:13], v[40:41], v[12:13], v[22:23]
	v_and_b32_sdwa v15, v4, v203 dst_sel:DWORD dst_unused:UNUSED_PAD src0_sel:WORD_1 src1_sel:DWORD
	v_and_b32_sdwa v19, v16, v203 dst_sel:DWORD dst_unused:UNUSED_PAD src0_sel:WORD_1 src1_sel:DWORD
	v_and_b32_sdwa v22, v7, v203 dst_sel:DWORD dst_unused:UNUSED_PAD src0_sel:WORD_1 src1_sel:DWORD
	v_and_b32_sdwa v23, v6, v203 dst_sel:DWORD dst_unused:UNUSED_PAD src0_sel:WORD_1 src1_sel:DWORD
	v_and_b32_sdwa v14, v5, v203 dst_sel:DWORD dst_unused:UNUSED_PAD src0_sel:WORD_1 src1_sel:DWORD
	v_and_b32_sdwa v18, v17, v203 dst_sel:DWORD dst_unused:UNUSED_PAD src0_sel:WORD_1 src1_sel:DWORD
	v_and_b32_sdwa v20, v13, v203 dst_sel:DWORD dst_unused:UNUSED_PAD src0_sel:WORD_1 src1_sel:DWORD
	v_and_b32_sdwa v21, v12, v203 dst_sel:DWORD dst_unused:UNUSED_PAD src0_sel:WORD_1 src1_sel:DWORD
	v_add3_u32 v4, v4, v15, s54
	v_add3_u32 v15, v16, v19, s54
	v_add3_u32 v7, v7, v22, s54
	v_add3_u32 v6, v6, v23, s54
	v_add3_u32 v5, v5, v14, s54
	v_add3_u32 v14, v17, v18, s54
	v_add3_u32 v12, v12, v21, s54
	v_add3_u32 v13, v13, v20, s54
	v_lshrrev_b32_e32 v4, 16, v4
	v_lshrrev_b32_e32 v15, 16, v15
	v_and_b32_e32 v7, 0xffff0000, v7
	v_and_b32_e32 v16, 0xffff0000, v6
	v_and_or_b32 v6, v5, s52, v4
	v_or_b32_sdwa v5, v7, v13 dst_sel:DWORD dst_unused:UNUSED_PAD src0_sel:DWORD src1_sel:WORD_1
	v_or_b32_sdwa v4, v16, v12 dst_sel:DWORD dst_unused:UNUSED_PAD src0_sel:DWORD src1_sel:WORD_1
	v_and_or_b32 v7, v14, s52, v15
	s_or_b64 exec, exec, s[18:19]
	ds_write_b128 v140, v[4:7]
	s_waitcnt vmcnt(10)
	v_add_u32_e32 v12, s51, v123
	v_cmp_gt_u32_e32 vcc, s37, v12
	s_nop 1
	v_cndmask_b32_e32 v7, 0, v63, vcc
	v_cndmask_b32_e32 v6, 0, v62, vcc
	v_cndmask_b32_e32 v5, 0, v61, vcc
	v_cndmask_b32_e32 v4, 0, v60, vcc
	v_lshlrev_b32_e32 v13, 16, v5
	v_lshlrev_b32_e32 v12, 16, v4
	v_and_b32_e32 v15, 0xffff0000, v5
	v_and_b32_e32 v14, 0xffff0000, v4
	v_and_b32_e32 v17, 0xffff0000, v6
	v_lshlrev_b32_e32 v16, 16, v6
	v_and_b32_e32 v19, 0xffff0000, v7
	v_lshlrev_b32_e32 v18, 16, v7
	ds_bpermute_b32 v26, v113, v12
	ds_bpermute_b32 v24, v113, v14
	ds_bpermute_b32 v27, v113, v13
	ds_bpermute_b32 v25, v113, v15
	ds_bpermute_b32 v22, v113, v16
	ds_bpermute_b32 v23, v113, v17
	ds_bpermute_b32 v20, v113, v18
	ds_bpermute_b32 v21, v113, v19
	s_and_saveexec_b64 s[18:19], s[46:47]
	s_waitcnt lgkmcnt(4)
	v_pk_mul_f32 v[24:25], v[88:89], v[24:25]
	s_waitcnt lgkmcnt(2)
	v_pk_mul_f32 v[22:23], v[88:89], v[22:23]
	s_waitcnt lgkmcnt(0)
	v_pk_mul_f32 v[20:21], v[88:89], v[20:21]
	v_pk_mul_f32 v[26:27], v[88:89], v[26:27]
	v_mov_b32_e32 v40, v228
	v_mov_b32_e32 v41, v230
	v_mov_b32_e32 v42, v236
	v_mov_b32_e32 v43, v238
	v_mov_b32_e32 v30, v237
	v_mov_b32_e32 v31, v239
	v_mov_b32_e32 v6, v229
	v_mov_b32_e32 v7, v231
	v_pk_mul_f32 v[4:5], v[22:23], v[172:173]
	v_pk_mul_f32 v[20:21], v[20:21], v[174:175]
	v_pk_mul_f32 v[24:25], v[24:25], v[30:31]
	v_pk_mul_f32 v[22:23], v[26:27], v[42:43]
	v_pk_fma_f32 v[4:5], v[232:233], v[16:17], v[4:5]
	v_pk_fma_f32 v[16:17], v[234:235], v[18:19], v[20:21]
	v_pk_fma_f32 v[6:7], v[6:7], v[14:15], v[24:25]
	v_pk_fma_f32 v[12:13], v[40:41], v[12:13], v[22:23]
	v_and_b32_sdwa v15, v4, v203 dst_sel:DWORD dst_unused:UNUSED_PAD src0_sel:WORD_1 src1_sel:DWORD
	v_and_b32_sdwa v19, v16, v203 dst_sel:DWORD dst_unused:UNUSED_PAD src0_sel:WORD_1 src1_sel:DWORD
	v_and_b32_sdwa v22, v7, v203 dst_sel:DWORD dst_unused:UNUSED_PAD src0_sel:WORD_1 src1_sel:DWORD
	v_and_b32_sdwa v23, v6, v203 dst_sel:DWORD dst_unused:UNUSED_PAD src0_sel:WORD_1 src1_sel:DWORD
	v_and_b32_sdwa v14, v5, v203 dst_sel:DWORD dst_unused:UNUSED_PAD src0_sel:WORD_1 src1_sel:DWORD
	v_and_b32_sdwa v18, v17, v203 dst_sel:DWORD dst_unused:UNUSED_PAD src0_sel:WORD_1 src1_sel:DWORD
	v_and_b32_sdwa v20, v13, v203 dst_sel:DWORD dst_unused:UNUSED_PAD src0_sel:WORD_1 src1_sel:DWORD
	v_and_b32_sdwa v21, v12, v203 dst_sel:DWORD dst_unused:UNUSED_PAD src0_sel:WORD_1 src1_sel:DWORD
	v_add3_u32 v4, v4, v15, s54
	v_add3_u32 v15, v16, v19, s54
	v_add3_u32 v7, v7, v22, s54
	v_add3_u32 v6, v6, v23, s54
	v_add3_u32 v5, v5, v14, s54
	v_add3_u32 v14, v17, v18, s54
	v_add3_u32 v12, v12, v21, s54
	v_add3_u32 v13, v13, v20, s54
	v_lshrrev_b32_e32 v4, 16, v4
	v_lshrrev_b32_e32 v15, 16, v15
	v_and_b32_e32 v7, 0xffff0000, v7
	v_and_b32_e32 v16, 0xffff0000, v6
	v_and_or_b32 v6, v5, s52, v4
	v_or_b32_sdwa v5, v7, v13 dst_sel:DWORD dst_unused:UNUSED_PAD src0_sel:DWORD src1_sel:WORD_1
	v_or_b32_sdwa v4, v16, v12 dst_sel:DWORD dst_unused:UNUSED_PAD src0_sel:DWORD src1_sel:WORD_1
	v_and_or_b32 v7, v14, s52, v15
	s_or_b64 exec, exec, s[18:19]
	ds_write_b128 v141, v[4:7]
	s_waitcnt vmcnt(6)
	v_add_u32_e32 v12, s51, v124
	v_cmp_gt_u32_e32 vcc, s37, v12
	s_nop 1
	v_cndmask_b32_e32 v7, 0, v67, vcc
	v_cndmask_b32_e32 v6, 0, v66, vcc
	v_cndmask_b32_e32 v5, 0, v65, vcc
	v_cndmask_b32_e32 v4, 0, v64, vcc
	v_lshlrev_b32_e32 v13, 16, v5
	v_lshlrev_b32_e32 v12, 16, v4
	v_and_b32_e32 v15, 0xffff0000, v5
	v_and_b32_e32 v14, 0xffff0000, v4
	v_and_b32_e32 v17, 0xffff0000, v6
	v_lshlrev_b32_e32 v16, 16, v6
	v_and_b32_e32 v19, 0xffff0000, v7
	v_lshlrev_b32_e32 v18, 16, v7
	ds_bpermute_b32 v26, v113, v12
	ds_bpermute_b32 v24, v113, v14
	ds_bpermute_b32 v27, v113, v13
	ds_bpermute_b32 v25, v113, v15
	ds_bpermute_b32 v22, v113, v16
	ds_bpermute_b32 v23, v113, v17
	ds_bpermute_b32 v20, v113, v18
	ds_bpermute_b32 v21, v113, v19
	s_and_saveexec_b64 s[18:19], s[46:47]
	s_waitcnt lgkmcnt(4)
	v_pk_mul_f32 v[24:25], v[88:89], v[24:25]
	s_waitcnt lgkmcnt(2)
	v_pk_mul_f32 v[22:23], v[88:89], v[22:23]
	s_waitcnt lgkmcnt(0)
	v_pk_mul_f32 v[20:21], v[88:89], v[20:21]
	v_pk_mul_f32 v[26:27], v[88:89], v[26:27]
	v_mov_b32_e32 v40, v68
	v_mov_b32_e32 v41, v70
	v_mov_b32_e32 v42, v76
	v_mov_b32_e32 v43, v78
	v_mov_b32_e32 v30, v77
	v_mov_b32_e32 v31, v79
	v_mov_b32_e32 v6, v69
	v_mov_b32_e32 v7, v71
	v_pk_mul_f32 v[4:5], v[22:23], v[80:81]
	v_pk_mul_f32 v[20:21], v[20:21], v[82:83]
	v_pk_mul_f32 v[24:25], v[24:25], v[30:31]
	v_pk_mul_f32 v[22:23], v[26:27], v[42:43]
	v_pk_fma_f32 v[4:5], v[72:73], v[16:17], v[4:5]
	v_pk_fma_f32 v[16:17], v[74:75], v[18:19], v[20:21]
	v_pk_fma_f32 v[6:7], v[6:7], v[14:15], v[24:25]
	v_pk_fma_f32 v[12:13], v[40:41], v[12:13], v[22:23]
	v_and_b32_sdwa v15, v4, v203 dst_sel:DWORD dst_unused:UNUSED_PAD src0_sel:WORD_1 src1_sel:DWORD
	v_and_b32_sdwa v19, v16, v203 dst_sel:DWORD dst_unused:UNUSED_PAD src0_sel:WORD_1 src1_sel:DWORD
	v_and_b32_sdwa v22, v7, v203 dst_sel:DWORD dst_unused:UNUSED_PAD src0_sel:WORD_1 src1_sel:DWORD
	v_and_b32_sdwa v23, v6, v203 dst_sel:DWORD dst_unused:UNUSED_PAD src0_sel:WORD_1 src1_sel:DWORD
	v_and_b32_sdwa v14, v5, v203 dst_sel:DWORD dst_unused:UNUSED_PAD src0_sel:WORD_1 src1_sel:DWORD
	v_and_b32_sdwa v18, v17, v203 dst_sel:DWORD dst_unused:UNUSED_PAD src0_sel:WORD_1 src1_sel:DWORD
	v_and_b32_sdwa v20, v13, v203 dst_sel:DWORD dst_unused:UNUSED_PAD src0_sel:WORD_1 src1_sel:DWORD
	v_and_b32_sdwa v21, v12, v203 dst_sel:DWORD dst_unused:UNUSED_PAD src0_sel:WORD_1 src1_sel:DWORD
	v_add3_u32 v4, v4, v15, s54
	v_add3_u32 v15, v16, v19, s54
	v_add3_u32 v7, v7, v22, s54
	v_add3_u32 v6, v6, v23, s54
	v_add3_u32 v5, v5, v14, s54
	v_add3_u32 v14, v17, v18, s54
	v_add3_u32 v12, v12, v21, s54
	v_add3_u32 v13, v13, v20, s54
	v_lshrrev_b32_e32 v4, 16, v4
	v_lshrrev_b32_e32 v15, 16, v15
	v_and_b32_e32 v7, 0xffff0000, v7
	v_and_b32_e32 v16, 0xffff0000, v6
	v_and_or_b32 v6, v5, s52, v4
	v_or_b32_sdwa v5, v7, v13 dst_sel:DWORD dst_unused:UNUSED_PAD src0_sel:DWORD src1_sel:WORD_1
	v_or_b32_sdwa v4, v16, v12 dst_sel:DWORD dst_unused:UNUSED_PAD src0_sel:DWORD src1_sel:WORD_1
	v_and_or_b32 v7, v14, s52, v15
	s_or_b64 exec, exec, s[18:19]
	ds_write_b128 v142, v[4:7]
	s_waitcnt vmcnt(5)
	v_add_u32_e32 v12, s51, v125
	v_cmp_gt_u32_e32 vcc, s37, v12
	s_nop 1
	v_cndmask_b32_e32 v4, 0, v44, vcc
	v_cndmask_b32_e32 v5, 0, v45, vcc
	v_cndmask_b32_e32 v6, 0, v46, vcc
	v_cndmask_b32_e32 v7, 0, v47, vcc
	ds_write_b16 v126, v4 offset:55296
	ds_write_b16_d16_hi v126, v4 offset:56080
	ds_write_b16 v126, v5 offset:56864
	ds_write_b16_d16_hi v126, v5 offset:57648
	ds_write_b16 v126, v6 offset:58432
	ds_write_b16_d16_hi v126, v6 offset:59216
	ds_write_b16 v126, v7 offset:60000
	ds_write_b16_d16_hi v126, v7 offset:60784
	s_waitcnt vmcnt(4)
	v_add_u32_e32 v12, s51, v127
	v_cmp_gt_u32_e32 vcc, s37, v12
	s_nop 1
	v_cndmask_b32_e32 v4, 0, v48, vcc
	v_cndmask_b32_e32 v5, 0, v49, vcc
	v_cndmask_b32_e32 v6, 0, v50, vcc
	v_cndmask_b32_e32 v7, 0, v51, vcc
	ds_write_b16 v128, v4 offset:56320
	ds_write_b16_d16_hi v128, v4 offset:57104
	ds_write_b16 v128, v5 offset:57888
	ds_write_b16_d16_hi v128, v5 offset:58672
	ds_write_b16 v128, v6 offset:59456
	ds_write_b16_d16_hi v128, v6 offset:60240
	ds_write_b16 v128, v7 offset:61024
	ds_write_b16_d16_hi v128, v7 offset:61808
	s_waitcnt vmcnt(3)
	v_add_u32_e32 v12, s51, v129
	v_cmp_gt_u32_e32 vcc, s37, v12
	s_nop 1
	v_cndmask_b32_e32 v4, 0, v176, vcc
	v_cndmask_b32_e32 v5, 0, v177, vcc
	v_cndmask_b32_e32 v6, 0, v178, vcc
	v_cndmask_b32_e32 v7, 0, v179, vcc
	ds_write_b16 v130, v4 offset:57344
	ds_write_b16_d16_hi v130, v4 offset:58128
	ds_write_b16 v130, v5 offset:58912
	ds_write_b16_d16_hi v130, v5 offset:59696
	ds_write_b16 v130, v6 offset:60480
	ds_write_b16_d16_hi v130, v6 offset:61264
	ds_write_b16 v130, v7 offset:62048
	ds_write_b16_d16_hi v130, v7 offset:62832
	s_waitcnt vmcnt(2)
	v_add_u32_e32 v12, s51, v131
	v_cmp_gt_u32_e32 vcc, s37, v12
	s_nop 1
	v_cndmask_b32_e32 v4, 0, v180, vcc
	v_cndmask_b32_e32 v5, 0, v181, vcc
	v_cndmask_b32_e32 v6, 0, v182, vcc
	v_cndmask_b32_e32 v7, 0, v183, vcc
	ds_write_b16 v132, v4 offset:58368
	ds_write_b16_d16_hi v132, v4 offset:59152
	ds_write_b16 v132, v5 offset:59936
	ds_write_b16_d16_hi v132, v5 offset:60720
	ds_write_b16 v132, v6 offset:61504
	ds_write_b16_d16_hi v132, v6 offset:62288
	ds_write_b16 v132, v7 offset:63072
	ds_write_b16_d16_hi v132, v7 offset:63856
	s_waitcnt vmcnt(1)
	v_add_u32_e32 v12, s51, v133
	v_cmp_gt_u32_e32 vcc, s37, v12
	s_nop 1
	v_cndmask_b32_e32 v4, 0, v184, vcc
	v_cndmask_b32_e32 v5, 0, v185, vcc
	v_cndmask_b32_e32 v6, 0, v186, vcc
	v_cndmask_b32_e32 v7, 0, v187, vcc
	ds_write_b16 v134, v4 offset:59392
	ds_write_b16_d16_hi v134, v4 offset:60176
	ds_write_b16 v134, v5 offset:60960
	ds_write_b16_d16_hi v134, v5 offset:61744
	ds_write_b16 v134, v6 offset:62528
	ds_write_b16_d16_hi v134, v6 offset:63312
	ds_write_b16 v134, v7 offset:64096
	ds_write_b16_d16_hi v134, v7 offset:64880
	s_waitcnt vmcnt(0)
	v_add_u32_e32 v12, s51, v135
	v_cmp_gt_u32_e32 vcc, s37, v12
	s_nop 1
	v_cndmask_b32_e32 v4, 0, v188, vcc
	v_cndmask_b32_e32 v5, 0, v189, vcc
	v_cndmask_b32_e32 v6, 0, v190, vcc
	v_cndmask_b32_e32 v7, 0, v191, vcc
	ds_write_b16 v136, v4 offset:60416
	ds_write_b16_d16_hi v136, v4 offset:61200
	ds_write_b16 v136, v5 offset:61984
	ds_write_b16_d16_hi v136, v5 offset:62768
	ds_write_b16 v136, v6 offset:63552
	ds_write_b16_d16_hi v136, v6 offset:64336
	ds_write_b16 v136, v7 offset:65120
	ds_write_b16_d16_hi v137, v7 offset:5488
	s_lshr_b32 s18, s45, 1
	s_and_b32 s18, s18, 63
	v_lshl_or_b32 v12, s18, 7, v112
	v_lshlrev_b32_e32 v152, 6, v12
	v_lshl_add_u64 v[108:109], s[12:13], 0, v[152:153]
	v_lshlrev_b32_e32 v152, 10, v12
	v_cndmask_b32_e64 v12, 0, 1, s[10:11]
	s_nop 1
	v_readfirstlane_b32 s18, v12
	s_nop 1
	s_lshl_b32 s18, s18, 8
	s_add_i32 s18, s44, s18
	s_ashr_i32 s19, s18, 31
	s_lshl_b64 s[18:19], s[18:19], 1
	s_ashr_i32 s17, s16, 31
	s_lshl_b64 s[16:17], s[16:17], 2
	v_readlane_b32 s8, v254, 0
	s_nop 1
	s_add_u32 s16, s8, s16
	v_readlane_b32 s8, v254, 1
	s_nop 1
	s_addc_u32 s17, s8, s17
	s_sub_i32 s60, 0x80, s50
	s_sub_i32 s61, 0x2080, s50
	s_lshl_b64 s[0:1], s[0:1], 23
	s_add_u32 s0, s18, s0
	s_addc_u32 s1, s19, s1
	s_mov_b32 s18, 0xd000
	s_mov_b32 s19, s21
	s_waitcnt lgkmcnt(0)
	s_barrier
	global_load_dword v4, v153, s[16:17]
	s_mov_b64 s[16:17], 0
	s_waitcnt vmcnt(0)
	v_mul_f32_e32 v143, 0x3fb8aa3b, v4
	v_lshl_add_u64 v[4:5], s[0:1], 0, v[152:153]
	v_lshl_add_u64 v[110:111], v[104:105], 0, v[4:5]
	s_branch .LBB0_579

.LBB0_705:
	s_add_u32 s44, s60, 0xfffe0080
	s_addc_u32 s45, s61, -1
	s_add_i32 s83, 0, 0x10000
	s_cmp_eq_u32 s82, 4
	s_cselect_b32 s63, s21, s45
	s_cselect_b32 s62, s78, s44
	s_cselect_b32 s45, s19, s81
	s_cselect_b32 s44, s79, s80
	s_add_i32 s86, 0, 0x14000
	v_add_u32_e32 v140, s83, v195
	v_add_u32_e32 v186, s86, v195
	ds_read_b128 v[124:127], v140
	ds_read_b128 v[132:135], v140 offset:1024
	ds_read_b128 v[136:139], v140 offset:2048
	ds_read_b128 v[140:143], v140 offset:3072
	ds_read_b128 v[144:147], v186
	ds_read_b128 v[148:151], v186 offset:1024
	ds_read_b128 v[182:185], v186 offset:2048
	ds_read_b128 v[186:189], v186 offset:3072
	v_lshl_add_u64 v[198:199], s[60:61], 0, v[180:181]
	s_add_i32 m0, s59, 0xc000
	ds_read_b128 v[190:193], v197
	ds_read_b128 v[210:213], v197 offset:1024
	ds_read_b128 v[214:217], v197 offset:2048
	ds_read_b128 v[218:221], v197 offset:3072
	ds_read_b128 v[224:227], v197 offset:4096
	ds_read_b128 v[228:231], v197 offset:5120
	ds_read_b128 v[232:235], v197 offset:6144
	ds_read_b128 v[236:239], v197 offset:7168
	global_load_lds_dwordx4 v[198:199], off
	v_lshl_add_u64 v[198:199], s[60:61], 0, v[178:179]
	s_add_i32 m0, s59, 0xe000
	s_nop 0
	global_load_lds_dwordx4 v[198:199], off
	s_waitcnt vmcnt(8)
	s_waitcnt lgkmcnt(0)
	s_barrier
	s_setprio 1
	s_waitcnt lgkmcnt(0)
	v_mfma_f32_16x16x32_bf16 v[128:131], v[124:127], v[190:193], v[128:131]
	v_mfma_f32_16x16x32_bf16 v[120:123], v[136:139], v[190:193], v[120:123]
	v_mfma_f32_16x16x32_bf16 v[108:111], v[124:127], v[214:217], v[108:111]
	v_mfma_f32_16x16x32_bf16 v[104:107], v[136:139], v[214:217], v[104:107]
	v_mfma_f32_16x16x32_bf16 v[92:95], v[124:127], v[224:227], v[92:95]
	v_mfma_f32_16x16x32_bf16 v[88:91], v[136:139], v[224:227], v[88:91]
	v_mfma_f32_16x16x32_bf16 v[76:79], v[124:127], v[232:235], v[76:79]
	v_mfma_f32_16x16x32_bf16 v[72:75], v[136:139], v[232:235], v[72:75]
	v_mfma_f32_16x16x32_bf16 v[128:131], v[132:135], v[210:213], v[128:131]
	v_mfma_f32_16x16x32_bf16 v[120:123], v[140:143], v[210:213], v[120:123]
	v_mfma_f32_16x16x32_bf16 v[108:111], v[132:135], v[218:221], v[108:111]
	v_mfma_f32_16x16x32_bf16 v[104:107], v[140:143], v[218:221], v[104:107]
	v_mfma_f32_16x16x32_bf16 v[92:95], v[132:135], v[228:231], v[92:95]
	v_mfma_f32_16x16x32_bf16 v[88:91], v[140:143], v[228:231], v[88:91]
	v_mfma_f32_16x16x32_bf16 v[76:79], v[132:135], v[236:239], v[76:79]
	v_mfma_f32_16x16x32_bf16 v[72:75], v[140:143], v[236:239], v[72:75]
	s_setprio 0
	s_setprio 1
	v_mfma_f32_16x16x32_bf16 v[116:119], v[144:147], v[190:193], v[116:119]
	v_mfma_f32_16x16x32_bf16 v[112:115], v[182:185], v[190:193], v[112:115]
	v_mfma_f32_16x16x32_bf16 v[100:103], v[144:147], v[214:217], v[100:103]
	v_mfma_f32_16x16x32_bf16 v[96:99], v[182:185], v[214:217], v[96:99]
	v_mfma_f32_16x16x32_bf16 v[84:87], v[144:147], v[224:227], v[84:87]
	v_mfma_f32_16x16x32_bf16 v[80:83], v[182:185], v[224:227], v[80:83]
	v_mfma_f32_16x16x32_bf16 v[68:71], v[144:147], v[232:235], v[68:71]
	v_mfma_f32_16x16x32_bf16 v[64:67], v[182:185], v[232:235], v[64:67]
	v_mfma_f32_16x16x32_bf16 v[116:119], v[148:151], v[210:213], v[116:119]
	v_mfma_f32_16x16x32_bf16 v[112:115], v[186:189], v[210:213], v[112:115]
	v_mfma_f32_16x16x32_bf16 v[100:103], v[148:151], v[218:221], v[100:103]
	v_mfma_f32_16x16x32_bf16 v[96:99], v[186:189], v[218:221], v[96:99]
	v_mfma_f32_16x16x32_bf16 v[84:87], v[148:151], v[228:231], v[84:87]
	v_mfma_f32_16x16x32_bf16 v[80:83], v[186:189], v[228:231], v[80:83]
	v_mfma_f32_16x16x32_bf16 v[68:71], v[148:151], v[236:239], v[68:71]
	v_mfma_f32_16x16x32_bf16 v[64:67], v[186:189], v[236:239], v[64:67]
	s_setprio 0
	s_barrier
	s_add_i32 s83, s83, s8
	v_lshl_add_u64 v[198:199], s[44:45], 0, v[152:153]
	s_mov_b32 m0, s83
	ds_read_b128 v[190:193], v197 offset:16384
	ds_read_b128 v[210:213], v197 offset:17408
	ds_read_b128 v[214:217], v197 offset:18432
	ds_read_b128 v[218:221], v197 offset:19456
	ds_read_b128 v[224:227], v197 offset:20480
	ds_read_b128 v[228:231], v197 offset:21504
	ds_read_b128 v[232:235], v197 offset:22528
	ds_read_b128 v[236:239], v197 offset:23552
	global_load_lds_dwordx4 v[198:199], off
	s_add_i32 m0, s83, 0x2000
	s_add_u32 s84, s44, 0x20000
	v_lshl_add_u64 v[240:241], s[44:45], 0, v[172:173]
	s_addc_u32 s85, s45, 0
	s_add_i32 s83, s86, s8
	global_load_lds_dwordx4 v[240:241], off
	v_lshl_add_u64 v[242:243], s[84:85], 0, v[152:153]
	s_mov_b32 m0, s83
	v_lshl_add_u64 v[244:245], s[62:63], 0, v[174:175]
	global_load_lds_dwordx4 v[242:243], off
	v_lshl_add_u64 v[242:243], s[84:85], 0, v[172:173]
	s_add_i32 m0, s83, 0x2000
	s_nop 0
	global_load_lds_dwordx4 v[242:243], off
	v_lshl_add_u64 v[242:243], s[62:63], 0, v[176:177]
	s_mov_b32 m0, s59
	s_nop 0
	global_load_lds_dwordx4 v[242:243], off
	s_mov_b32 m0, s66
	s_nop 0
	global_load_lds_dwordx4 v[244:245], off
	s_waitcnt vmcnt(8)
	s_waitcnt lgkmcnt(0)
	s_barrier
	s_setprio 1
	s_waitcnt lgkmcnt(0)
	v_mfma_f32_16x16x32_bf16 v[60:63], v[124:127], v[190:193], v[60:63]
	v_mfma_f32_16x16x32_bf16 v[56:59], v[136:139], v[190:193], v[56:59]
	v_mfma_f32_16x16x32_bf16 v[48:51], v[124:127], v[214:217], v[48:51]
	v_mfma_f32_16x16x32_bf16 v[40:43], v[136:139], v[214:217], v[40:43]
	v_mfma_f32_16x16x32_bf16 v[32:35], v[124:127], v[224:227], v[32:35]
	v_mfma_f32_16x16x32_bf16 v[24:27], v[136:139], v[224:227], v[24:27]
	v_mfma_f32_16x16x32_bf16 v[16:19], v[124:127], v[232:235], v[16:19]
	v_mfma_f32_16x16x32_bf16 v[8:11], v[136:139], v[232:235], v[8:11]
	v_mfma_f32_16x16x32_bf16 v[60:63], v[132:135], v[210:213], v[60:63]
	v_mfma_f32_16x16x32_bf16 v[56:59], v[140:143], v[210:213], v[56:59]
	v_mfma_f32_16x16x32_bf16 v[48:51], v[132:135], v[218:221], v[48:51]
	v_mfma_f32_16x16x32_bf16 v[40:43], v[140:143], v[218:221], v[40:43]
	v_mfma_f32_16x16x32_bf16 v[32:35], v[132:135], v[228:231], v[32:35]
	v_mfma_f32_16x16x32_bf16 v[24:27], v[140:143], v[228:231], v[24:27]
	v_mfma_f32_16x16x32_bf16 v[16:19], v[132:135], v[236:239], v[16:19]
	v_mfma_f32_16x16x32_bf16 v[8:11], v[140:143], v[236:239], v[8:11]
	s_setprio 0
	s_setprio 1
	v_mfma_f32_16x16x32_bf16 v[52:55], v[144:147], v[190:193], v[52:55]
	v_mfma_f32_16x16x32_bf16 v[44:47], v[182:185], v[190:193], v[44:47]
	v_mfma_f32_16x16x32_bf16 v[36:39], v[144:147], v[214:217], v[36:39]
	v_mfma_f32_16x16x32_bf16 v[28:31], v[182:185], v[214:217], v[28:31]
	v_mfma_f32_16x16x32_bf16 v[20:23], v[144:147], v[224:227], v[20:23]
	v_mfma_f32_16x16x32_bf16 v[12:15], v[182:185], v[224:227], v[12:15]
	v_mfma_f32_16x16x32_bf16 v[4:7], v[144:147], v[232:235], v[4:7]
	v_mfma_f32_16x16x32_bf16 v[0:3], v[182:185], v[232:235], v[0:3]
	v_mfma_f32_16x16x32_bf16 v[52:55], v[148:151], v[210:213], v[52:55]
	v_mfma_f32_16x16x32_bf16 v[44:47], v[186:189], v[210:213], v[44:47]
	v_mfma_f32_16x16x32_bf16 v[36:39], v[148:151], v[218:221], v[36:39]
	v_mfma_f32_16x16x32_bf16 v[28:31], v[186:189], v[218:221], v[28:31]
	v_mfma_f32_16x16x32_bf16 v[20:23], v[148:151], v[228:231], v[20:23]
	v_mfma_f32_16x16x32_bf16 v[12:15], v[186:189], v[228:231], v[12:15]
	v_mfma_f32_16x16x32_bf16 v[4:7], v[148:151], v[236:239], v[4:7]
	v_mfma_f32_16x16x32_bf16 v[0:3], v[186:189], v[236:239], v[0:3]
	s_setprio 0
	s_barrier
	s_add_i32 s83, 0, 0x18000
	s_add_i32 s84, 0, 0x1c000
	v_add_u32_e32 v140, s83, v195
	v_add_u32_e32 v186, s84, v195
	ds_read_b128 v[124:127], v140
	ds_read_b128 v[132:135], v140 offset:1024
	ds_read_b128 v[136:139], v140 offset:2048
	ds_read_b128 v[140:143], v140 offset:3072
	ds_read_b128 v[144:147], v186
	ds_read_b128 v[148:151], v186 offset:1024
	ds_read_b128 v[182:185], v186 offset:2048
	ds_read_b128 v[186:189], v186 offset:3072
	s_add_u32 s62, s62, 0x20000
	s_addc_u32 s63, s63, 0
	s_mov_b32 m0, s67
	v_lshl_add_u64 v[246:247], s[62:63], 0, v[176:177]
	ds_read_b128 v[190:193], v197 offset:32768
	ds_read_b128 v[210:213], v197 offset:33792
	ds_read_b128 v[214:217], v197 offset:34816
	ds_read_b128 v[218:221], v197 offset:35840
	ds_read_b128 v[224:227], v197 offset:36864
	ds_read_b128 v[228:231], v197 offset:37888
	ds_read_b128 v[232:235], v197 offset:38912
	ds_read_b128 v[236:239], v197 offset:39936
	global_load_lds_dwordx4 v[246:247], off
	v_lshl_add_u64 v[246:247], s[62:63], 0, v[174:175]
	s_mov_b32 m0, s68
	s_nop 0
	global_load_lds_dwordx4 v[246:247], off
	s_waitcnt vmcnt(8)
	s_waitcnt lgkmcnt(0)
	s_barrier
	s_setprio 1
	s_waitcnt lgkmcnt(0)
	v_mfma_f32_16x16x32_bf16 v[128:131], v[124:127], v[190:193], v[128:131]
	v_mfma_f32_16x16x32_bf16 v[120:123], v[136:139], v[190:193], v[120:123]
	v_mfma_f32_16x16x32_bf16 v[108:111], v[124:127], v[214:217], v[108:111]
	v_mfma_f32_16x16x32_bf16 v[104:107], v[136:139], v[214:217], v[104:107]
	v_mfma_f32_16x16x32_bf16 v[92:95], v[124:127], v[224:227], v[92:95]
	v_mfma_f32_16x16x32_bf16 v[88:91], v[136:139], v[224:227], v[88:91]
	v_mfma_f32_16x16x32_bf16 v[76:79], v[124:127], v[232:235], v[76:79]
	v_mfma_f32_16x16x32_bf16 v[72:75], v[136:139], v[232:235], v[72:75]
	v_mfma_f32_16x16x32_bf16 v[128:131], v[132:135], v[210:213], v[128:131]
	v_mfma_f32_16x16x32_bf16 v[120:123], v[140:143], v[210:213], v[120:123]
	v_mfma_f32_16x16x32_bf16 v[108:111], v[132:135], v[218:221], v[108:111]
	v_mfma_f32_16x16x32_bf16 v[104:107], v[140:143], v[218:221], v[104:107]
	v_mfma_f32_16x16x32_bf16 v[92:95], v[132:135], v[228:231], v[92:95]
	v_mfma_f32_16x16x32_bf16 v[88:91], v[140:143], v[228:231], v[88:91]
	v_mfma_f32_16x16x32_bf16 v[76:79], v[132:135], v[236:239], v[76:79]
	v_mfma_f32_16x16x32_bf16 v[72:75], v[140:143], v[236:239], v[72:75]
	s_setprio 0
	s_setprio 1
	v_mfma_f32_16x16x32_bf16 v[116:119], v[144:147], v[190:193], v[116:119]
	v_mfma_f32_16x16x32_bf16 v[112:115], v[182:185], v[190:193], v[112:115]
	v_mfma_f32_16x16x32_bf16 v[100:103], v[144:147], v[214:217], v[100:103]
	v_mfma_f32_16x16x32_bf16 v[96:99], v[182:185], v[214:217], v[96:99]
	v_mfma_f32_16x16x32_bf16 v[84:87], v[144:147], v[224:227], v[84:87]
	v_mfma_f32_16x16x32_bf16 v[80:83], v[182:185], v[224:227], v[80:83]
	v_mfma_f32_16x16x32_bf16 v[68:71], v[144:147], v[232:235], v[68:71]
	v_mfma_f32_16x16x32_bf16 v[64:67], v[182:185], v[232:235], v[64:67]
	v_mfma_f32_16x16x32_bf16 v[116:119], v[148:151], v[210:213], v[116:119]
	v_mfma_f32_16x16x32_bf16 v[112:115], v[186:189], v[210:213], v[112:115]
	v_mfma_f32_16x16x32_bf16 v[100:103], v[148:151], v[218:221], v[100:103]
	v_mfma_f32_16x16x32_bf16 v[96:99], v[186:189], v[218:221], v[96:99]
	v_mfma_f32_16x16x32_bf16 v[84:87], v[148:151], v[228:231], v[84:87]
	v_mfma_f32_16x16x32_bf16 v[80:83], v[186:189], v[228:231], v[80:83]
	v_mfma_f32_16x16x32_bf16 v[68:71], v[148:151], v[236:239], v[68:71]
	v_mfma_f32_16x16x32_bf16 v[64:67], v[186:189], v[236:239], v[64:67]
	s_setprio 0
	s_barrier
	s_add_i32 s62, s83, s8
	v_lshl_add_u64 v[198:199], v[198:199], 0, s[22:23]
	s_mov_b32 m0, s62
	ds_read_b128 v[190:193], v197 offset:49152
	ds_read_b128 v[210:213], v197 offset:50176
	ds_read_b128 v[214:217], v197 offset:51200
	ds_read_b128 v[218:221], v197 offset:52224
	ds_read_b128 v[224:227], v197 offset:53248
	ds_read_b128 v[228:231], v197 offset:54272
	ds_read_b128 v[232:235], v197 offset:55296
	ds_read_b128 v[236:239], v197 offset:56320
	global_load_lds_dwordx4 v[198:199], off
	s_add_i32 m0, s62, 0x2000
	s_add_u32 s44, s44, 0x20080
	v_lshl_add_u64 v[198:199], v[240:241], 0, s[22:23]
	s_addc_u32 s45, s45, 0
	s_add_i32 s62, s84, s8
	global_load_lds_dwordx4 v[198:199], off
	v_lshl_add_u64 v[198:199], s[44:45], 0, v[152:153]
	s_mov_b32 m0, s62
	s_nop 0
	global_load_lds_dwordx4 v[198:199], off
	v_lshl_add_u64 v[198:199], s[44:45], 0, v[172:173]
	s_add_i32 m0, s62, 0x2000
	s_nop 0
	global_load_lds_dwordx4 v[198:199], off
	v_lshl_add_u64 v[198:199], v[242:243], 0, s[22:23]
	s_mov_b32 m0, s69
	s_nop 0
	global_load_lds_dwordx4 v[198:199], off
	v_lshl_add_u64 v[198:199], v[244:245], 0, s[22:23]
	s_mov_b32 m0, s74
	s_nop 0
	global_load_lds_dwordx4 v[198:199], off
	s_waitcnt vmcnt(8)
	s_waitcnt lgkmcnt(0)
	s_barrier
	s_setprio 1
	s_waitcnt lgkmcnt(0)
	v_mfma_f32_16x16x32_bf16 v[60:63], v[124:127], v[190:193], v[60:63]
	v_mfma_f32_16x16x32_bf16 v[56:59], v[136:139], v[190:193], v[56:59]
	v_mfma_f32_16x16x32_bf16 v[48:51], v[124:127], v[214:217], v[48:51]
	v_mfma_f32_16x16x32_bf16 v[40:43], v[136:139], v[214:217], v[40:43]
	v_mfma_f32_16x16x32_bf16 v[32:35], v[124:127], v[224:227], v[32:35]
	v_mfma_f32_16x16x32_bf16 v[24:27], v[136:139], v[224:227], v[24:27]
	v_mfma_f32_16x16x32_bf16 v[16:19], v[124:127], v[232:235], v[16:19]
	v_mfma_f32_16x16x32_bf16 v[8:11], v[136:139], v[232:235], v[8:11]
	v_mfma_f32_16x16x32_bf16 v[60:63], v[132:135], v[210:213], v[60:63]
	v_mfma_f32_16x16x32_bf16 v[56:59], v[140:143], v[210:213], v[56:59]
	v_mfma_f32_16x16x32_bf16 v[48:51], v[132:135], v[218:221], v[48:51]
	v_mfma_f32_16x16x32_bf16 v[40:43], v[140:143], v[218:221], v[40:43]
	v_mfma_f32_16x16x32_bf16 v[32:35], v[132:135], v[228:231], v[32:35]
	v_mfma_f32_16x16x32_bf16 v[24:27], v[140:143], v[228:231], v[24:27]
	v_mfma_f32_16x16x32_bf16 v[16:19], v[132:135], v[236:239], v[16:19]
	v_mfma_f32_16x16x32_bf16 v[8:11], v[140:143], v[236:239], v[8:11]
	s_setprio 0
	s_setprio 1
	v_mfma_f32_16x16x32_bf16 v[52:55], v[144:147], v[190:193], v[52:55]
	v_mfma_f32_16x16x32_bf16 v[44:47], v[182:185], v[190:193], v[44:47]
	v_mfma_f32_16x16x32_bf16 v[36:39], v[144:147], v[214:217], v[36:39]
	v_mfma_f32_16x16x32_bf16 v[28:31], v[182:185], v[214:217], v[28:31]
	v_mfma_f32_16x16x32_bf16 v[20:23], v[144:147], v[224:227], v[20:23]
	v_mfma_f32_16x16x32_bf16 v[12:15], v[182:185], v[224:227], v[12:15]
	v_mfma_f32_16x16x32_bf16 v[4:7], v[144:147], v[232:235], v[4:7]
	v_mfma_f32_16x16x32_bf16 v[0:3], v[182:185], v[232:235], v[0:3]
	v_mfma_f32_16x16x32_bf16 v[52:55], v[148:151], v[210:213], v[52:55]
	v_mfma_f32_16x16x32_bf16 v[44:47], v[186:189], v[210:213], v[44:47]
	v_mfma_f32_16x16x32_bf16 v[36:39], v[148:151], v[218:221], v[36:39]
	v_mfma_f32_16x16x32_bf16 v[28:31], v[186:189], v[218:221], v[28:31]
	v_mfma_f32_16x16x32_bf16 v[20:23], v[148:151], v[228:231], v[20:23]
	v_mfma_f32_16x16x32_bf16 v[12:15], v[186:189], v[228:231], v[12:15]
	v_mfma_f32_16x16x32_bf16 v[4:7], v[148:151], v[236:239], v[4:7]
	v_mfma_f32_16x16x32_bf16 v[0:3], v[186:189], v[236:239], v[0:3]
	s_setprio 0
	s_barrier
	s_add_i32 s82, s82, 2
	s_add_u32 s80, s80, 0x100
	s_addc_u32 s81, s81, 0
	s_add_u32 s60, s60, 0x100
	s_addc_u32 s61, s61, 0
	s_cmp_gt_u32 s82, 5
	s_cbranch_scc0 .LBB0_705
	s_and_b64 vcc, exec, s[16:17]
	s_cbranch_vccz .LBB0_708
	s_barrier

.LBB0_725:
	s_add_u32 s44, s60, 0xfffe0080
	s_addc_u32 s45, s61, -1
	s_add_i32 s83, 0, 0x10000
	s_cmp_eq_u32 s82, 4
	s_cselect_b32 s63, s21, s45
	s_cselect_b32 s62, s78, s44
	s_cselect_b32 s45, s19, s81
	s_cselect_b32 s44, s79, s80
	s_add_i32 s86, 0, 0x14000
	v_add_u32_e32 v140, s83, v181
	v_add_u32_e32 v178, s86, v181
	ds_read_b128 v[128:131], v140
	ds_read_b128 v[132:135], v140 offset:1024
	ds_read_b128 v[136:139], v140 offset:2048
	ds_read_b128 v[140:143], v140 offset:3072
	ds_read_b128 v[174:177], v178
	ds_read_b128 v[184:187], v178 offset:1024
	ds_read_b128 v[188:191], v178 offset:2048
	ds_read_b128 v[192:195], v178 offset:3072
	v_lshl_add_u64 v[178:179], s[60:61], 0, v[172:173]
	s_add_i32 m0, s59, 0xc000
	ds_read_b128 v[196:199], v183
	ds_read_b128 v[210:213], v183 offset:1024
	ds_read_b128 v[214:217], v183 offset:2048
	ds_read_b128 v[218:221], v183 offset:3072
	ds_read_b128 v[224:227], v183 offset:4096
	ds_read_b128 v[228:231], v183 offset:5120
	ds_read_b128 v[232:235], v183 offset:6144
	ds_read_b128 v[236:239], v183 offset:7168
	global_load_lds_dwordx4 v[178:179], off
	v_lshl_add_u64 v[178:179], s[60:61], 0, v[150:151]
	s_add_i32 m0, s59, 0xe000
	s_nop 0
	global_load_lds_dwordx4 v[178:179], off
	s_waitcnt vmcnt(8)
	s_waitcnt lgkmcnt(0)
	s_barrier
	s_setprio 1
	s_waitcnt lgkmcnt(0)
	v_mfma_f32_16x16x32_bf16 v[124:127], v[128:131], v[196:199], v[124:127]
	v_mfma_f32_16x16x32_bf16 v[120:123], v[136:139], v[196:199], v[120:123]
	v_mfma_f32_16x16x32_bf16 v[108:111], v[128:131], v[214:217], v[108:111]
	v_mfma_f32_16x16x32_bf16 v[104:107], v[136:139], v[214:217], v[104:107]
	v_mfma_f32_16x16x32_bf16 v[92:95], v[128:131], v[224:227], v[92:95]
	v_mfma_f32_16x16x32_bf16 v[88:91], v[136:139], v[224:227], v[88:91]
	v_mfma_f32_16x16x32_bf16 v[76:79], v[128:131], v[232:235], v[76:79]
	v_mfma_f32_16x16x32_bf16 v[72:75], v[136:139], v[232:235], v[72:75]
	v_mfma_f32_16x16x32_bf16 v[124:127], v[132:135], v[210:213], v[124:127]
	v_mfma_f32_16x16x32_bf16 v[120:123], v[140:143], v[210:213], v[120:123]
	v_mfma_f32_16x16x32_bf16 v[108:111], v[132:135], v[218:221], v[108:111]
	v_mfma_f32_16x16x32_bf16 v[104:107], v[140:143], v[218:221], v[104:107]
	v_mfma_f32_16x16x32_bf16 v[92:95], v[132:135], v[228:231], v[92:95]
	v_mfma_f32_16x16x32_bf16 v[88:91], v[140:143], v[228:231], v[88:91]
	v_mfma_f32_16x16x32_bf16 v[76:79], v[132:135], v[236:239], v[76:79]
	v_mfma_f32_16x16x32_bf16 v[72:75], v[140:143], v[236:239], v[72:75]
	s_setprio 0
	s_setprio 1
	v_mfma_f32_16x16x32_bf16 v[116:119], v[174:177], v[196:199], v[116:119]
	v_mfma_f32_16x16x32_bf16 v[112:115], v[188:191], v[196:199], v[112:115]
	v_mfma_f32_16x16x32_bf16 v[100:103], v[174:177], v[214:217], v[100:103]
	v_mfma_f32_16x16x32_bf16 v[96:99], v[188:191], v[214:217], v[96:99]
	v_mfma_f32_16x16x32_bf16 v[84:87], v[174:177], v[224:227], v[84:87]
	v_mfma_f32_16x16x32_bf16 v[80:83], v[188:191], v[224:227], v[80:83]
	v_mfma_f32_16x16x32_bf16 v[68:71], v[174:177], v[232:235], v[68:71]
	v_mfma_f32_16x16x32_bf16 v[64:67], v[188:191], v[232:235], v[64:67]
	v_mfma_f32_16x16x32_bf16 v[116:119], v[184:187], v[210:213], v[116:119]
	v_mfma_f32_16x16x32_bf16 v[112:115], v[192:195], v[210:213], v[112:115]
	v_mfma_f32_16x16x32_bf16 v[100:103], v[184:187], v[218:221], v[100:103]
	v_mfma_f32_16x16x32_bf16 v[96:99], v[192:195], v[218:221], v[96:99]
	v_mfma_f32_16x16x32_bf16 v[84:87], v[184:187], v[228:231], v[84:87]
	v_mfma_f32_16x16x32_bf16 v[80:83], v[192:195], v[228:231], v[80:83]
	v_mfma_f32_16x16x32_bf16 v[68:71], v[184:187], v[236:239], v[68:71]
	v_mfma_f32_16x16x32_bf16 v[64:67], v[192:195], v[236:239], v[64:67]
	s_setprio 0
	s_barrier
	s_add_i32 s83, s83, s8
	v_lshl_add_u64 v[178:179], s[44:45], 0, v[152:153]
	s_mov_b32 m0, s83
	ds_read_b128 v[196:199], v183 offset:16384
	ds_read_b128 v[210:213], v183 offset:17408
	ds_read_b128 v[214:217], v183 offset:18432
	ds_read_b128 v[218:221], v183 offset:19456
	ds_read_b128 v[224:227], v183 offset:20480
	ds_read_b128 v[228:231], v183 offset:21504
	ds_read_b128 v[232:235], v183 offset:22528
	ds_read_b128 v[236:239], v183 offset:23552
	global_load_lds_dwordx4 v[178:179], off
	s_add_i32 m0, s83, 0x2000
	s_add_u32 s84, s44, 0x20000
	v_lshl_add_u64 v[240:241], s[44:45], 0, v[144:145]
	s_addc_u32 s85, s45, 0
	s_add_i32 s83, s86, s8
	global_load_lds_dwordx4 v[240:241], off
	v_lshl_add_u64 v[242:243], s[84:85], 0, v[152:153]
	s_mov_b32 m0, s83
	v_lshl_add_u64 v[244:245], s[62:63], 0, v[146:147]
	global_load_lds_dwordx4 v[242:243], off
	v_lshl_add_u64 v[242:243], s[84:85], 0, v[144:145]
	s_add_i32 m0, s83, 0x2000
	s_nop 0
	global_load_lds_dwordx4 v[242:243], off
	v_lshl_add_u64 v[242:243], s[62:63], 0, v[148:149]
	s_mov_b32 m0, s59
	s_nop 0
	global_load_lds_dwordx4 v[242:243], off
	s_mov_b32 m0, s66
	s_nop 0
	global_load_lds_dwordx4 v[244:245], off
	s_waitcnt vmcnt(8)
	s_waitcnt lgkmcnt(0)
	s_barrier
	s_setprio 1
	s_waitcnt lgkmcnt(0)
	v_mfma_f32_16x16x32_bf16 v[60:63], v[128:131], v[196:199], v[60:63]
	v_mfma_f32_16x16x32_bf16 v[56:59], v[136:139], v[196:199], v[56:59]
	v_mfma_f32_16x16x32_bf16 v[44:47], v[128:131], v[214:217], v[44:47]
	v_mfma_f32_16x16x32_bf16 v[40:43], v[136:139], v[214:217], v[40:43]
	v_mfma_f32_16x16x32_bf16 v[28:31], v[128:131], v[224:227], v[28:31]
	v_mfma_f32_16x16x32_bf16 v[24:27], v[136:139], v[224:227], v[24:27]
	v_mfma_f32_16x16x32_bf16 v[12:15], v[128:131], v[232:235], v[12:15]
	v_mfma_f32_16x16x32_bf16 v[8:11], v[136:139], v[232:235], v[8:11]
	v_mfma_f32_16x16x32_bf16 v[60:63], v[132:135], v[210:213], v[60:63]
	v_mfma_f32_16x16x32_bf16 v[56:59], v[140:143], v[210:213], v[56:59]
	v_mfma_f32_16x16x32_bf16 v[44:47], v[132:135], v[218:221], v[44:47]
	v_mfma_f32_16x16x32_bf16 v[40:43], v[140:143], v[218:221], v[40:43]
	v_mfma_f32_16x16x32_bf16 v[28:31], v[132:135], v[228:231], v[28:31]
	v_mfma_f32_16x16x32_bf16 v[24:27], v[140:143], v[228:231], v[24:27]
	v_mfma_f32_16x16x32_bf16 v[12:15], v[132:135], v[236:239], v[12:15]
	v_mfma_f32_16x16x32_bf16 v[8:11], v[140:143], v[236:239], v[8:11]
	s_setprio 0
	s_setprio 1
	v_mfma_f32_16x16x32_bf16 v[52:55], v[174:177], v[196:199], v[52:55]
	v_mfma_f32_16x16x32_bf16 v[48:51], v[188:191], v[196:199], v[48:51]
	v_mfma_f32_16x16x32_bf16 v[36:39], v[174:177], v[214:217], v[36:39]
	v_mfma_f32_16x16x32_bf16 v[32:35], v[188:191], v[214:217], v[32:35]
	v_mfma_f32_16x16x32_bf16 v[20:23], v[174:177], v[224:227], v[20:23]
	v_mfma_f32_16x16x32_bf16 v[16:19], v[188:191], v[224:227], v[16:19]
	v_mfma_f32_16x16x32_bf16 v[4:7], v[174:177], v[232:235], v[4:7]
	v_mfma_f32_16x16x32_bf16 v[0:3], v[188:191], v[232:235], v[0:3]
	v_mfma_f32_16x16x32_bf16 v[52:55], v[184:187], v[210:213], v[52:55]
	v_mfma_f32_16x16x32_bf16 v[48:51], v[192:195], v[210:213], v[48:51]
	v_mfma_f32_16x16x32_bf16 v[36:39], v[184:187], v[218:221], v[36:39]
	v_mfma_f32_16x16x32_bf16 v[32:35], v[192:195], v[218:221], v[32:35]
	v_mfma_f32_16x16x32_bf16 v[20:23], v[184:187], v[228:231], v[20:23]
	v_mfma_f32_16x16x32_bf16 v[16:19], v[192:195], v[228:231], v[16:19]
	v_mfma_f32_16x16x32_bf16 v[4:7], v[184:187], v[236:239], v[4:7]
	v_mfma_f32_16x16x32_bf16 v[0:3], v[192:195], v[236:239], v[0:3]
	s_setprio 0
	s_barrier
	s_add_i32 s83, 0, 0x18000
	s_add_i32 s84, 0, 0x1c000
	v_add_u32_e32 v140, s83, v181
	v_add_u32_e32 v192, s84, v181
	ds_read_b128 v[128:131], v140
	ds_read_b128 v[132:135], v140 offset:1024
	ds_read_b128 v[136:139], v140 offset:2048
	ds_read_b128 v[140:143], v140 offset:3072
	ds_read_b128 v[174:177], v192
	ds_read_b128 v[184:187], v192 offset:1024
	ds_read_b128 v[188:191], v192 offset:2048
	ds_read_b128 v[192:195], v192 offset:3072
	s_add_u32 s62, s62, 0x20000
	s_addc_u32 s63, s63, 0
	s_mov_b32 m0, s67
	v_lshl_add_u64 v[246:247], s[62:63], 0, v[148:149]
	ds_read_b128 v[196:199], v183 offset:32768
	ds_read_b128 v[210:213], v183 offset:33792
	ds_read_b128 v[214:217], v183 offset:34816
	ds_read_b128 v[218:221], v183 offset:35840
	ds_read_b128 v[224:227], v183 offset:36864
	ds_read_b128 v[228:231], v183 offset:37888
	ds_read_b128 v[232:235], v183 offset:38912
	ds_read_b128 v[236:239], v183 offset:39936
	global_load_lds_dwordx4 v[246:247], off
	v_lshl_add_u64 v[246:247], s[62:63], 0, v[146:147]
	s_mov_b32 m0, s68
	s_nop 0
	global_load_lds_dwordx4 v[246:247], off
	s_waitcnt vmcnt(8)
	s_waitcnt lgkmcnt(0)
	s_barrier
	s_setprio 1
	s_waitcnt lgkmcnt(0)
	v_mfma_f32_16x16x32_bf16 v[124:127], v[128:131], v[196:199], v[124:127]
	v_mfma_f32_16x16x32_bf16 v[120:123], v[136:139], v[196:199], v[120:123]
	v_mfma_f32_16x16x32_bf16 v[108:111], v[128:131], v[214:217], v[108:111]
	v_mfma_f32_16x16x32_bf16 v[104:107], v[136:139], v[214:217], v[104:107]
	v_mfma_f32_16x16x32_bf16 v[92:95], v[128:131], v[224:227], v[92:95]
	v_mfma_f32_16x16x32_bf16 v[88:91], v[136:139], v[224:227], v[88:91]
	v_mfma_f32_16x16x32_bf16 v[76:79], v[128:131], v[232:235], v[76:79]
	v_mfma_f32_16x16x32_bf16 v[72:75], v[136:139], v[232:235], v[72:75]
	v_mfma_f32_16x16x32_bf16 v[124:127], v[132:135], v[210:213], v[124:127]
	v_mfma_f32_16x16x32_bf16 v[120:123], v[140:143], v[210:213], v[120:123]
	v_mfma_f32_16x16x32_bf16 v[108:111], v[132:135], v[218:221], v[108:111]
	v_mfma_f32_16x16x32_bf16 v[104:107], v[140:143], v[218:221], v[104:107]
	v_mfma_f32_16x16x32_bf16 v[92:95], v[132:135], v[228:231], v[92:95]
	v_mfma_f32_16x16x32_bf16 v[88:91], v[140:143], v[228:231], v[88:91]
	v_mfma_f32_16x16x32_bf16 v[76:79], v[132:135], v[236:239], v[76:79]
	v_mfma_f32_16x16x32_bf16 v[72:75], v[140:143], v[236:239], v[72:75]
	s_setprio 0
	s_setprio 1
	v_mfma_f32_16x16x32_bf16 v[116:119], v[174:177], v[196:199], v[116:119]
	v_mfma_f32_16x16x32_bf16 v[112:115], v[188:191], v[196:199], v[112:115]
	v_mfma_f32_16x16x32_bf16 v[100:103], v[174:177], v[214:217], v[100:103]
	v_mfma_f32_16x16x32_bf16 v[96:99], v[188:191], v[214:217], v[96:99]
	v_mfma_f32_16x16x32_bf16 v[84:87], v[174:177], v[224:227], v[84:87]
	v_mfma_f32_16x16x32_bf16 v[80:83], v[188:191], v[224:227], v[80:83]
	v_mfma_f32_16x16x32_bf16 v[68:71], v[174:177], v[232:235], v[68:71]
	v_mfma_f32_16x16x32_bf16 v[64:67], v[188:191], v[232:235], v[64:67]
	v_mfma_f32_16x16x32_bf16 v[116:119], v[184:187], v[210:213], v[116:119]
	v_mfma_f32_16x16x32_bf16 v[112:115], v[192:195], v[210:213], v[112:115]
	v_mfma_f32_16x16x32_bf16 v[100:103], v[184:187], v[218:221], v[100:103]
	v_mfma_f32_16x16x32_bf16 v[96:99], v[192:195], v[218:221], v[96:99]
	v_mfma_f32_16x16x32_bf16 v[84:87], v[184:187], v[228:231], v[84:87]
	v_mfma_f32_16x16x32_bf16 v[80:83], v[192:195], v[228:231], v[80:83]
	v_mfma_f32_16x16x32_bf16 v[68:71], v[184:187], v[236:239], v[68:71]
	v_mfma_f32_16x16x32_bf16 v[64:67], v[192:195], v[236:239], v[64:67]
	s_setprio 0
	s_barrier
	s_add_i32 s62, s83, s8
	v_lshl_add_u64 v[178:179], v[178:179], 0, s[22:23]
	s_mov_b32 m0, s62
	ds_read_b128 v[196:199], v183 offset:49152
	ds_read_b128 v[210:213], v183 offset:50176
	ds_read_b128 v[214:217], v183 offset:51200
	ds_read_b128 v[218:221], v183 offset:52224
	ds_read_b128 v[224:227], v183 offset:53248
	ds_read_b128 v[228:231], v183 offset:54272
	ds_read_b128 v[232:235], v183 offset:55296
	ds_read_b128 v[236:239], v183 offset:56320
	global_load_lds_dwordx4 v[178:179], off
	s_add_i32 m0, s62, 0x2000
	s_add_u32 s44, s44, 0x20080
	v_lshl_add_u64 v[178:179], v[240:241], 0, s[22:23]
	s_addc_u32 s45, s45, 0
	s_add_i32 s62, s84, s8
	global_load_lds_dwordx4 v[178:179], off
	v_lshl_add_u64 v[178:179], s[44:45], 0, v[152:153]
	s_mov_b32 m0, s62
	s_nop 0
	global_load_lds_dwordx4 v[178:179], off
	v_lshl_add_u64 v[178:179], s[44:45], 0, v[144:145]
	s_add_i32 m0, s62, 0x2000
	s_nop 0
	global_load_lds_dwordx4 v[178:179], off
	v_lshl_add_u64 v[178:179], v[242:243], 0, s[22:23]
	s_mov_b32 m0, s69
	s_nop 0
	global_load_lds_dwordx4 v[178:179], off
	v_lshl_add_u64 v[178:179], v[244:245], 0, s[22:23]
	s_mov_b32 m0, s74
	s_nop 0
	global_load_lds_dwordx4 v[178:179], off
	s_waitcnt vmcnt(8)
	s_waitcnt lgkmcnt(0)
	s_barrier
	s_setprio 1
	s_waitcnt lgkmcnt(0)
	v_mfma_f32_16x16x32_bf16 v[60:63], v[128:131], v[196:199], v[60:63]
	v_mfma_f32_16x16x32_bf16 v[56:59], v[136:139], v[196:199], v[56:59]
	v_mfma_f32_16x16x32_bf16 v[44:47], v[128:131], v[214:217], v[44:47]
	v_mfma_f32_16x16x32_bf16 v[40:43], v[136:139], v[214:217], v[40:43]
	v_mfma_f32_16x16x32_bf16 v[28:31], v[128:131], v[224:227], v[28:31]
	v_mfma_f32_16x16x32_bf16 v[24:27], v[136:139], v[224:227], v[24:27]
	v_mfma_f32_16x16x32_bf16 v[12:15], v[128:131], v[232:235], v[12:15]
	v_mfma_f32_16x16x32_bf16 v[8:11], v[136:139], v[232:235], v[8:11]
	v_mfma_f32_16x16x32_bf16 v[60:63], v[132:135], v[210:213], v[60:63]
	v_mfma_f32_16x16x32_bf16 v[56:59], v[140:143], v[210:213], v[56:59]
	v_mfma_f32_16x16x32_bf16 v[44:47], v[132:135], v[218:221], v[44:47]
	v_mfma_f32_16x16x32_bf16 v[40:43], v[140:143], v[218:221], v[40:43]
	v_mfma_f32_16x16x32_bf16 v[28:31], v[132:135], v[228:231], v[28:31]
	v_mfma_f32_16x16x32_bf16 v[24:27], v[140:143], v[228:231], v[24:27]
	v_mfma_f32_16x16x32_bf16 v[12:15], v[132:135], v[236:239], v[12:15]
	v_mfma_f32_16x16x32_bf16 v[8:11], v[140:143], v[236:239], v[8:11]
	s_setprio 0
	s_setprio 1
	v_mfma_f32_16x16x32_bf16 v[52:55], v[174:177], v[196:199], v[52:55]
	v_mfma_f32_16x16x32_bf16 v[48:51], v[188:191], v[196:199], v[48:51]
	v_mfma_f32_16x16x32_bf16 v[36:39], v[174:177], v[214:217], v[36:39]
	v_mfma_f32_16x16x32_bf16 v[32:35], v[188:191], v[214:217], v[32:35]
	v_mfma_f32_16x16x32_bf16 v[20:23], v[174:177], v[224:227], v[20:23]
	v_mfma_f32_16x16x32_bf16 v[16:19], v[188:191], v[224:227], v[16:19]
	v_mfma_f32_16x16x32_bf16 v[4:7], v[174:177], v[232:235], v[4:7]
	v_mfma_f32_16x16x32_bf16 v[0:3], v[188:191], v[232:235], v[0:3]
	v_mfma_f32_16x16x32_bf16 v[52:55], v[184:187], v[210:213], v[52:55]
	v_mfma_f32_16x16x32_bf16 v[48:51], v[192:195], v[210:213], v[48:51]
	v_mfma_f32_16x16x32_bf16 v[36:39], v[184:187], v[218:221], v[36:39]
	v_mfma_f32_16x16x32_bf16 v[32:35], v[192:195], v[218:221], v[32:35]
	v_mfma_f32_16x16x32_bf16 v[20:23], v[184:187], v[228:231], v[20:23]
	v_mfma_f32_16x16x32_bf16 v[16:19], v[192:195], v[228:231], v[16:19]
	v_mfma_f32_16x16x32_bf16 v[4:7], v[184:187], v[236:239], v[4:7]
	v_mfma_f32_16x16x32_bf16 v[0:3], v[192:195], v[236:239], v[0:3]
	s_setprio 0
	s_barrier
	s_add_i32 s82, s82, 2
	s_add_u32 s80, s80, 0x100
	s_addc_u32 s81, s81, 0
	s_add_u32 s60, s60, 0x100
	s_addc_u32 s61, s61, 0
	s_cmp_gt_u32 s82, 5
	s_cbranch_scc0 .LBB0_725
	s_and_b64 vcc, exec, s[16:17]
	s_cbranch_vccz .LBB0_728
	s_barrier

.LBB0_822:
	s_add_u32 s62, s60, 0xfffc0080
	s_addc_u32 s63, s61, -1
	s_add_i32 s86, 0, 0x10000
	s_cmp_eq_u32 s85, 12
	s_cselect_b32 s67, s21, s63
	s_cselect_b32 s66, s81, s62
	s_cselect_b32 s63, s19, s84
	s_cselect_b32 s62, s82, s83
	s_add_i32 s89, 0, 0x14000
	v_add_u32_e32 v124, s86, v210
	v_add_u32_e32 v186, s89, v210
	ds_read_b128 v[112:115], v124
	ds_read_b128 v[116:119], v124 offset:1024
	ds_read_b128 v[120:123], v124 offset:2048
	ds_read_b128 v[124:127], v124 offset:3072
	ds_read_b128 v[132:135], v186
	ds_read_b128 v[140:143], v186 offset:1024
	ds_read_b128 v[182:185], v186 offset:2048
	ds_read_b128 v[186:189], v186 offset:3072
	v_lshl_add_u64 v[198:199], s[60:61], 0, v[180:181]
	s_add_i32 m0, s68, 0xc000
	ds_read_b128 v[190:193], v212
	ds_read_b128 v[194:197], v212 offset:1024
	ds_read_b128 v[214:217], v212 offset:2048
	ds_read_b128 v[218:221], v212 offset:3072
	ds_read_b128 v[224:227], v212 offset:4096
	ds_read_b128 v[228:231], v212 offset:5120
	ds_read_b128 v[232:235], v212 offset:6144
	ds_read_b128 v[236:239], v212 offset:7168
	global_load_lds_dwordx4 v[198:199], off
	v_lshl_add_u64 v[198:199], s[60:61], 0, v[178:179]
	s_add_i32 m0, s68, 0xe000
	s_nop 0
	global_load_lds_dwordx4 v[198:199], off
	s_waitcnt vmcnt(8)
	s_waitcnt lgkmcnt(0)
	s_barrier
	s_setprio 1
	s_waitcnt lgkmcnt(0)
	v_mfma_f32_16x16x32_bf16 v[148:151], v[112:115], v[190:193], v[148:151]
	v_mfma_f32_16x16x32_bf16 v[144:147], v[120:123], v[190:193], v[144:147]
	v_mfma_f32_16x16x32_bf16 v[108:111], v[112:115], v[214:217], v[108:111]
	v_mfma_f32_16x16x32_bf16 v[104:107], v[120:123], v[214:217], v[104:107]
	v_mfma_f32_16x16x32_bf16 v[92:95], v[112:115], v[224:227], v[92:95]
	v_mfma_f32_16x16x32_bf16 v[88:91], v[120:123], v[224:227], v[88:91]
	v_mfma_f32_16x16x32_bf16 v[76:79], v[112:115], v[232:235], v[76:79]
	v_mfma_f32_16x16x32_bf16 v[72:75], v[120:123], v[232:235], v[72:75]
	v_mfma_f32_16x16x32_bf16 v[148:151], v[116:119], v[194:197], v[148:151]
	v_mfma_f32_16x16x32_bf16 v[144:147], v[124:127], v[194:197], v[144:147]
	v_mfma_f32_16x16x32_bf16 v[108:111], v[116:119], v[218:221], v[108:111]
	v_mfma_f32_16x16x32_bf16 v[104:107], v[124:127], v[218:221], v[104:107]
	v_mfma_f32_16x16x32_bf16 v[92:95], v[116:119], v[228:231], v[92:95]
	v_mfma_f32_16x16x32_bf16 v[88:91], v[124:127], v[228:231], v[88:91]
	v_mfma_f32_16x16x32_bf16 v[76:79], v[116:119], v[236:239], v[76:79]
	v_mfma_f32_16x16x32_bf16 v[72:75], v[124:127], v[236:239], v[72:75]
	s_setprio 0
	s_setprio 1
	v_mfma_f32_16x16x32_bf16 v[136:139], v[132:135], v[190:193], v[136:139]
	v_mfma_f32_16x16x32_bf16 v[128:131], v[182:185], v[190:193], v[128:131]
	v_mfma_f32_16x16x32_bf16 v[100:103], v[132:135], v[214:217], v[100:103]
	v_mfma_f32_16x16x32_bf16 v[96:99], v[182:185], v[214:217], v[96:99]
	v_mfma_f32_16x16x32_bf16 v[84:87], v[132:135], v[224:227], v[84:87]
	v_mfma_f32_16x16x32_bf16 v[80:83], v[182:185], v[224:227], v[80:83]
	v_mfma_f32_16x16x32_bf16 v[68:71], v[132:135], v[232:235], v[68:71]
	v_mfma_f32_16x16x32_bf16 v[64:67], v[182:185], v[232:235], v[64:67]
	v_mfma_f32_16x16x32_bf16 v[136:139], v[140:143], v[194:197], v[136:139]
	v_mfma_f32_16x16x32_bf16 v[128:131], v[186:189], v[194:197], v[128:131]
	v_mfma_f32_16x16x32_bf16 v[100:103], v[140:143], v[218:221], v[100:103]
	v_mfma_f32_16x16x32_bf16 v[96:99], v[186:189], v[218:221], v[96:99]
	v_mfma_f32_16x16x32_bf16 v[84:87], v[140:143], v[228:231], v[84:87]
	v_mfma_f32_16x16x32_bf16 v[80:83], v[186:189], v[228:231], v[80:83]
	v_mfma_f32_16x16x32_bf16 v[68:71], v[140:143], v[236:239], v[68:71]
	v_mfma_f32_16x16x32_bf16 v[64:67], v[186:189], v[236:239], v[64:67]
	s_setprio 0
	s_barrier
	s_add_i32 s86, s86, s59
	v_lshl_add_u64 v[198:199], s[62:63], 0, v[152:153]
	s_mov_b32 m0, s86
	ds_read_b128 v[190:193], v212 offset:16384
	ds_read_b128 v[194:197], v212 offset:17408
	ds_read_b128 v[214:217], v212 offset:18432
	ds_read_b128 v[218:221], v212 offset:19456
	ds_read_b128 v[224:227], v212 offset:20480
	ds_read_b128 v[228:231], v212 offset:21504
	ds_read_b128 v[232:235], v212 offset:22528
	ds_read_b128 v[236:239], v212 offset:23552
	global_load_lds_dwordx4 v[198:199], off
	s_add_i32 m0, s86, 0x2000
	s_add_u32 s86, s62, 0x40000
	v_lshl_add_u64 v[240:241], s[62:63], 0, v[172:173]
	s_addc_u32 s87, s63, 0
	s_add_i32 s89, s89, s59
	global_load_lds_dwordx4 v[240:241], off
	v_lshl_add_u64 v[242:243], s[86:87], 0, v[152:153]
	s_mov_b32 m0, s89
	v_lshl_add_u64 v[244:245], s[66:67], 0, v[174:175]
	global_load_lds_dwordx4 v[242:243], off
	v_lshl_add_u64 v[242:243], s[86:87], 0, v[172:173]
	s_add_i32 m0, s89, 0x2000
	s_nop 0
	global_load_lds_dwordx4 v[242:243], off
	v_lshl_add_u64 v[242:243], s[66:67], 0, v[176:177]
	s_mov_b32 m0, s68
	s_nop 0
	global_load_lds_dwordx4 v[242:243], off
	s_mov_b32 m0, s69
	s_nop 0
	global_load_lds_dwordx4 v[244:245], off
	s_waitcnt vmcnt(8)
	s_waitcnt lgkmcnt(0)
	s_barrier
	s_setprio 1
	s_waitcnt lgkmcnt(0)
	v_mfma_f32_16x16x32_bf16 v[60:63], v[112:115], v[190:193], v[60:63]
	v_mfma_f32_16x16x32_bf16 v[56:59], v[120:123], v[190:193], v[56:59]
	v_mfma_f32_16x16x32_bf16 v[44:47], v[112:115], v[214:217], v[44:47]
	v_mfma_f32_16x16x32_bf16 v[40:43], v[120:123], v[214:217], v[40:43]
	v_mfma_f32_16x16x32_bf16 v[28:31], v[112:115], v[224:227], v[28:31]
	v_mfma_f32_16x16x32_bf16 v[24:27], v[120:123], v[224:227], v[24:27]
	v_mfma_f32_16x16x32_bf16 v[12:15], v[112:115], v[232:235], v[12:15]
	v_mfma_f32_16x16x32_bf16 v[8:11], v[120:123], v[232:235], v[8:11]
	v_mfma_f32_16x16x32_bf16 v[60:63], v[116:119], v[194:197], v[60:63]
	v_mfma_f32_16x16x32_bf16 v[56:59], v[124:127], v[194:197], v[56:59]
	v_mfma_f32_16x16x32_bf16 v[44:47], v[116:119], v[218:221], v[44:47]
	v_mfma_f32_16x16x32_bf16 v[40:43], v[124:127], v[218:221], v[40:43]
	v_mfma_f32_16x16x32_bf16 v[28:31], v[116:119], v[228:231], v[28:31]
	v_mfma_f32_16x16x32_bf16 v[24:27], v[124:127], v[228:231], v[24:27]
	v_mfma_f32_16x16x32_bf16 v[12:15], v[116:119], v[236:239], v[12:15]
	v_mfma_f32_16x16x32_bf16 v[8:11], v[124:127], v[236:239], v[8:11]
	s_setprio 0
	s_setprio 1
	v_mfma_f32_16x16x32_bf16 v[52:55], v[132:135], v[190:193], v[52:55]
	v_mfma_f32_16x16x32_bf16 v[48:51], v[182:185], v[190:193], v[48:51]
	v_mfma_f32_16x16x32_bf16 v[36:39], v[132:135], v[214:217], v[36:39]
	v_mfma_f32_16x16x32_bf16 v[32:35], v[182:185], v[214:217], v[32:35]
	v_mfma_f32_16x16x32_bf16 v[20:23], v[132:135], v[224:227], v[20:23]
	v_mfma_f32_16x16x32_bf16 v[16:19], v[182:185], v[224:227], v[16:19]
	v_mfma_f32_16x16x32_bf16 v[4:7], v[132:135], v[232:235], v[4:7]
	v_mfma_f32_16x16x32_bf16 v[0:3], v[182:185], v[232:235], v[0:3]
	v_mfma_f32_16x16x32_bf16 v[52:55], v[140:143], v[194:197], v[52:55]
	v_mfma_f32_16x16x32_bf16 v[48:51], v[186:189], v[194:197], v[48:51]
	v_mfma_f32_16x16x32_bf16 v[36:39], v[140:143], v[218:221], v[36:39]
	v_mfma_f32_16x16x32_bf16 v[32:35], v[186:189], v[218:221], v[32:35]
	v_mfma_f32_16x16x32_bf16 v[20:23], v[140:143], v[228:231], v[20:23]
	v_mfma_f32_16x16x32_bf16 v[16:19], v[186:189], v[228:231], v[16:19]
	v_mfma_f32_16x16x32_bf16 v[4:7], v[140:143], v[236:239], v[4:7]
	v_mfma_f32_16x16x32_bf16 v[0:3], v[186:189], v[236:239], v[0:3]
	s_setprio 0
	s_barrier
	s_add_i32 s86, 0, 0x18000
	s_add_i32 s87, 0, 0x1c000
	v_add_u32_e32 v124, s86, v210
	v_add_u32_e32 v186, s87, v210
	ds_read_b128 v[112:115], v124
	ds_read_b128 v[116:119], v124 offset:1024
	ds_read_b128 v[120:123], v124 offset:2048
	ds_read_b128 v[124:127], v124 offset:3072
	ds_read_b128 v[132:135], v186
	ds_read_b128 v[140:143], v186 offset:1024
	ds_read_b128 v[182:185], v186 offset:2048
	ds_read_b128 v[186:189], v186 offset:3072
	s_add_u32 s66, s66, 0x40000
	s_addc_u32 s67, s67, 0
	s_mov_b32 m0, s74
	v_lshl_add_u64 v[246:247], s[66:67], 0, v[176:177]
	ds_read_b128 v[190:193], v212 offset:32768
	ds_read_b128 v[194:197], v212 offset:33792
	ds_read_b128 v[214:217], v212 offset:34816
	ds_read_b128 v[218:221], v212 offset:35840
	ds_read_b128 v[224:227], v212 offset:36864
	ds_read_b128 v[228:231], v212 offset:37888
	ds_read_b128 v[232:235], v212 offset:38912
	ds_read_b128 v[236:239], v212 offset:39936
	global_load_lds_dwordx4 v[246:247], off
	v_lshl_add_u64 v[246:247], s[66:67], 0, v[174:175]
	s_mov_b32 m0, s75
	s_nop 0
	global_load_lds_dwordx4 v[246:247], off
	s_waitcnt vmcnt(8)
	s_waitcnt lgkmcnt(0)
	s_barrier
	s_setprio 1
	s_waitcnt lgkmcnt(0)
	v_mfma_f32_16x16x32_bf16 v[148:151], v[112:115], v[190:193], v[148:151]
	v_mfma_f32_16x16x32_bf16 v[144:147], v[120:123], v[190:193], v[144:147]
	v_mfma_f32_16x16x32_bf16 v[108:111], v[112:115], v[214:217], v[108:111]
	v_mfma_f32_16x16x32_bf16 v[104:107], v[120:123], v[214:217], v[104:107]
	v_mfma_f32_16x16x32_bf16 v[92:95], v[112:115], v[224:227], v[92:95]
	v_mfma_f32_16x16x32_bf16 v[88:91], v[120:123], v[224:227], v[88:91]
	v_mfma_f32_16x16x32_bf16 v[76:79], v[112:115], v[232:235], v[76:79]
	v_mfma_f32_16x16x32_bf16 v[72:75], v[120:123], v[232:235], v[72:75]
	v_mfma_f32_16x16x32_bf16 v[148:151], v[116:119], v[194:197], v[148:151]
	v_mfma_f32_16x16x32_bf16 v[144:147], v[124:127], v[194:197], v[144:147]
	v_mfma_f32_16x16x32_bf16 v[108:111], v[116:119], v[218:221], v[108:111]
	v_mfma_f32_16x16x32_bf16 v[104:107], v[124:127], v[218:221], v[104:107]
	v_mfma_f32_16x16x32_bf16 v[92:95], v[116:119], v[228:231], v[92:95]
	v_mfma_f32_16x16x32_bf16 v[88:91], v[124:127], v[228:231], v[88:91]
	v_mfma_f32_16x16x32_bf16 v[76:79], v[116:119], v[236:239], v[76:79]
	v_mfma_f32_16x16x32_bf16 v[72:75], v[124:127], v[236:239], v[72:75]
	s_setprio 0
	s_setprio 1
	v_mfma_f32_16x16x32_bf16 v[136:139], v[132:135], v[190:193], v[136:139]
	v_mfma_f32_16x16x32_bf16 v[128:131], v[182:185], v[190:193], v[128:131]
	v_mfma_f32_16x16x32_bf16 v[100:103], v[132:135], v[214:217], v[100:103]
	v_mfma_f32_16x16x32_bf16 v[96:99], v[182:185], v[214:217], v[96:99]
	v_mfma_f32_16x16x32_bf16 v[84:87], v[132:135], v[224:227], v[84:87]
	v_mfma_f32_16x16x32_bf16 v[80:83], v[182:185], v[224:227], v[80:83]
	v_mfma_f32_16x16x32_bf16 v[68:71], v[132:135], v[232:235], v[68:71]
	v_mfma_f32_16x16x32_bf16 v[64:67], v[182:185], v[232:235], v[64:67]
	v_mfma_f32_16x16x32_bf16 v[136:139], v[140:143], v[194:197], v[136:139]
	v_mfma_f32_16x16x32_bf16 v[128:131], v[186:189], v[194:197], v[128:131]
	v_mfma_f32_16x16x32_bf16 v[100:103], v[140:143], v[218:221], v[100:103]
	v_mfma_f32_16x16x32_bf16 v[96:99], v[186:189], v[218:221], v[96:99]
	v_mfma_f32_16x16x32_bf16 v[84:87], v[140:143], v[228:231], v[84:87]
	v_mfma_f32_16x16x32_bf16 v[80:83], v[186:189], v[228:231], v[80:83]
	v_mfma_f32_16x16x32_bf16 v[68:71], v[140:143], v[236:239], v[68:71]
	v_mfma_f32_16x16x32_bf16 v[64:67], v[186:189], v[236:239], v[64:67]
	s_setprio 0
	s_barrier
	s_add_i32 s66, s86, s59
	v_lshl_add_u64 v[198:199], v[198:199], 0, s[22:23]
	s_mov_b32 m0, s66
	ds_read_b128 v[190:193], v212 offset:49152
	ds_read_b128 v[194:197], v212 offset:50176
	ds_read_b128 v[214:217], v212 offset:51200
	ds_read_b128 v[218:221], v212 offset:52224
	ds_read_b128 v[224:227], v212 offset:53248
	ds_read_b128 v[228:231], v212 offset:54272
	ds_read_b128 v[232:235], v212 offset:55296
	ds_read_b128 v[236:239], v212 offset:56320
	global_load_lds_dwordx4 v[198:199], off
	s_add_i32 m0, s66, 0x2000
	s_add_u32 s62, s62, 0x40080
	v_lshl_add_u64 v[198:199], v[240:241], 0, s[22:23]
	s_addc_u32 s63, s63, 0
	s_add_i32 s66, s87, s59
	global_load_lds_dwordx4 v[198:199], off
	v_lshl_add_u64 v[198:199], s[62:63], 0, v[152:153]
	s_mov_b32 m0, s66
	s_nop 0
	global_load_lds_dwordx4 v[198:199], off
	v_lshl_add_u64 v[198:199], s[62:63], 0, v[172:173]
	s_add_i32 m0, s66, 0x2000
	s_nop 0
	global_load_lds_dwordx4 v[198:199], off
	v_lshl_add_u64 v[198:199], v[242:243], 0, s[22:23]
	s_mov_b32 m0, s77
	s_nop 0
	global_load_lds_dwordx4 v[198:199], off
	v_lshl_add_u64 v[198:199], v[244:245], 0, s[22:23]
	s_mov_b32 m0, s78
	s_nop 0
	global_load_lds_dwordx4 v[198:199], off
	s_waitcnt vmcnt(8)
	s_waitcnt lgkmcnt(0)
	s_barrier
	s_setprio 1
	s_waitcnt lgkmcnt(0)
	v_mfma_f32_16x16x32_bf16 v[60:63], v[112:115], v[190:193], v[60:63]
	v_mfma_f32_16x16x32_bf16 v[56:59], v[120:123], v[190:193], v[56:59]
	v_mfma_f32_16x16x32_bf16 v[44:47], v[112:115], v[214:217], v[44:47]
	v_mfma_f32_16x16x32_bf16 v[40:43], v[120:123], v[214:217], v[40:43]
	v_mfma_f32_16x16x32_bf16 v[28:31], v[112:115], v[224:227], v[28:31]
	v_mfma_f32_16x16x32_bf16 v[24:27], v[120:123], v[224:227], v[24:27]
	v_mfma_f32_16x16x32_bf16 v[12:15], v[112:115], v[232:235], v[12:15]
	v_mfma_f32_16x16x32_bf16 v[8:11], v[120:123], v[232:235], v[8:11]
	v_mfma_f32_16x16x32_bf16 v[60:63], v[116:119], v[194:197], v[60:63]
	v_mfma_f32_16x16x32_bf16 v[56:59], v[124:127], v[194:197], v[56:59]
	v_mfma_f32_16x16x32_bf16 v[44:47], v[116:119], v[218:221], v[44:47]
	v_mfma_f32_16x16x32_bf16 v[40:43], v[124:127], v[218:221], v[40:43]
	v_mfma_f32_16x16x32_bf16 v[28:31], v[116:119], v[228:231], v[28:31]
	v_mfma_f32_16x16x32_bf16 v[24:27], v[124:127], v[228:231], v[24:27]
	v_mfma_f32_16x16x32_bf16 v[12:15], v[116:119], v[236:239], v[12:15]
	v_mfma_f32_16x16x32_bf16 v[8:11], v[124:127], v[236:239], v[8:11]
	s_setprio 0
	s_setprio 1
	v_mfma_f32_16x16x32_bf16 v[52:55], v[132:135], v[190:193], v[52:55]
	v_mfma_f32_16x16x32_bf16 v[48:51], v[182:185], v[190:193], v[48:51]
	v_mfma_f32_16x16x32_bf16 v[36:39], v[132:135], v[214:217], v[36:39]
	v_mfma_f32_16x16x32_bf16 v[32:35], v[182:185], v[214:217], v[32:35]
	v_mfma_f32_16x16x32_bf16 v[20:23], v[132:135], v[224:227], v[20:23]
	v_mfma_f32_16x16x32_bf16 v[16:19], v[182:185], v[224:227], v[16:19]
	v_mfma_f32_16x16x32_bf16 v[4:7], v[132:135], v[232:235], v[4:7]
	v_mfma_f32_16x16x32_bf16 v[0:3], v[182:185], v[232:235], v[0:3]
	v_mfma_f32_16x16x32_bf16 v[52:55], v[140:143], v[194:197], v[52:55]
	v_mfma_f32_16x16x32_bf16 v[48:51], v[186:189], v[194:197], v[48:51]
	v_mfma_f32_16x16x32_bf16 v[36:39], v[140:143], v[218:221], v[36:39]
	v_mfma_f32_16x16x32_bf16 v[32:35], v[186:189], v[218:221], v[32:35]
	v_mfma_f32_16x16x32_bf16 v[20:23], v[140:143], v[228:231], v[20:23]
	v_mfma_f32_16x16x32_bf16 v[16:19], v[186:189], v[228:231], v[16:19]
	v_mfma_f32_16x16x32_bf16 v[4:7], v[140:143], v[236:239], v[4:7]
	v_mfma_f32_16x16x32_bf16 v[0:3], v[186:189], v[236:239], v[0:3]
	s_setprio 0
	s_barrier
	s_add_i32 s85, s85, 2
	s_add_u32 s83, s83, 0x100
	s_addc_u32 s84, s84, 0
	s_add_u32 s60, s60, 0x100
	s_addc_u32 s61, s61, 0
	s_cmp_gt_u32 s85, 13
	s_cbranch_scc0 .LBB0_822
	s_and_b64 vcc, exec, s[16:17]
	s_cbranch_vccz .LBB0_825
	s_barrier
